# K-loop barrier edges: setprio hoisted before the pre-MFMA barrier, redundant post-barrier lgkmcnt(0) dropped, setprio 0 after the closing barrier; plus MFMA fold and sc1 swiglu stores
# speedup vs baseline: 1.0224x; 1.0158x over previous
; #define PG8_STAGE(bufoff, gbase, voff) do { _Pragma("unroll") for (int _i = 0; _i < 2; ++_i) \
;         __builtin_amdgcn_global_load_lds((const unsigned*)((const char*)(gbase) + (voff)[_i]), (PG8_LAS unsigned*)(lds + (bufoff) + ldsw + _i * 8192), 16, 0, PG8_AUX_##voff); } while (0)
; #define PG8_LDA(dst, b, h) do { _Pragma("unroll") for (int m = 0; m < 4; ++m) _Pragma("unroll") for (int k = 0; k < 2; ++k) dst[m][k] = *(const PG8_LAS bf16x8*)(lds + PG8_SA(b, h) + aoff + m * 2048 + k * 1024); } while (0)
; #define PG8_LDB(dst, b, h) do { _Pragma("unroll") for (int n = 0; n < 2; ++n) _Pragma("unroll") for (int k = 0; k < 2; ++k) dst[n][k] = *(const PG8_LAS bf16x8*)(lds + PG8_SB(b, h) + boff + n * 2048 + k * 1024); } while (0)
; #define PG8_MMA(ai, bj, At, Bt) do { __builtin_amdgcn_s_setprio(1); _Pragma("unroll") for (int m = 0; m < 4; ++m) _Pragma("unroll") for (int n = 0; n < 2; ++n) _Pragma("unroll") for (int k = 0; k < 2; ++k) \
;         acc[ai][bj][m][n] = __builtin_amdgcn_mfma_f32_16x16x32_bf16(Bt[n][k], At[m][k], acc[ai][bj][m][n], 0, 0, 0); __builtin_amdgcn_s_setprio(0); } while (0)
; #define PG8_WAIT_V(n) asm volatile("s_waitcnt vmcnt(" #n ")" ::: "memory")
; #define PG8_WAIT_L(n) asm volatile("s_waitcnt lgkmcnt(" #n ")" ::: "memory")
; #define PG8_BAR __builtin_amdgcn_s_barrier()
; #define PG8_SCHED __builtin_amdgcn_sched_barrier(0)
;     ...
;             PG8_LDB(B0, 0, 0); PG8_LDB(B1, 0, 1); PG8_SCHED; PG8_LDA(At, 0, 0); PG8_STAGE(PG8_SA(1, 1), a1 + hstep, voffA);
;             PG8_WAIT_V(8); PG8_WAIT_L(0); PG8_BAR; PG8_MMA(0, 0, At, B0); PG8_MMA(0, 1, At, B1); PG8_BAR; PG8_SCHED;
;             PG8_LDA(At, 0, 1); PG8_STAGE(PG8_SB(0, 0), b2, voffB); PG8_STAGE(PG8_SB(0, 1), b2 + hstep, voffB); PG8_STAGE(PG8_SA(0, 0), a2, voffA);
;             PG8_WAIT_V(8); PG8_WAIT_L(0); PG8_BAR; PG8_MMA(1, 0, At, B0); PG8_MMA(1, 1, At, B1); PG8_BAR; PG8_SCHED;
.LBB0_582:
	s_lshl_b32 s30, s56, 7
	s_add_u32 s36, s22, s30
	s_addc_u32 s37, s23, 0
	s_add_i32 s35, s56, 2
	s_lshl_b32 s38, s35, 7
	s_add_u32 s39, s22, s38
	s_addc_u32 s57, s23, 0
	s_and_b64 s[30:31], s[28:29], exec
	s_cselect_b32 s31, s11, s57
	s_cselect_b32 s30, s53, s39
	s_add_u32 s38, s20, s38
	s_addc_u32 s39, s21, 0
	s_and_b64 s[28:29], s[28:29], exec
	s_cselect_b32 s29, s13, s39
	s_cselect_b32 s28, s54, s38
	s_add_i32 s38, 0, 0x10000
	v_add_u32_e32 v138, s38, v142
	s_add_i32 s39, 0, 0x14000
	ds_read_b128 v[146:149], v138
	ds_read_b128 v[150:153], v138 offset:1024
	ds_read_b128 v[154:157], v138 offset:2048
	ds_read_b128 v[158:161], v138 offset:3072
	v_add_u32_e32 v138, s39, v142
	ds_read_b128 v[162:165], v138
	ds_read_b128 v[166:169], v138 offset:1024
	ds_read_b128 v[170:173], v138 offset:2048
	ds_read_b128 v[174:177], v138 offset:3072
	s_add_u32 s36, s36, 0x80080
	s_addc_u32 s37, s37, 0
	v_lshl_add_u64 v[138:139], s[36:37], 0, v[130:131]
	s_add_i32 m0, s44, 0xc000
	ds_read_b128 v[178:181], v144
	ds_read_b128 v[182:185], v144 offset:1024
	ds_read_b128 v[186:189], v144 offset:2048
	ds_read_b128 v[190:193], v144 offset:3072
	ds_read_b128 v[200:203], v144 offset:4096
	ds_read_b128 v[204:207], v144 offset:5120
	ds_read_b128 v[208:211], v144 offset:6144
	ds_read_b128 v[212:215], v144 offset:7168
	global_load_lds_dwordx4 v[138:139], off
	v_lshl_add_u64 v[138:139], s[36:37], 0, v[134:135]
	s_add_i32 m0, s44, 0xe000
	s_nop 0
	global_load_lds_dwordx4 v[138:139], off
	s_waitcnt vmcnt(8)
	s_waitcnt lgkmcnt(0)
	s_setprio 1
	s_barrier
	v_mfma_f32_16x16x32_bf16 v[126:129], v[146:149], v[178:181], v[126:129]
	v_mfma_f32_16x16x32_bf16 v[118:121], v[154:157], v[178:181], v[118:121]
	v_mfma_f32_16x16x32_bf16 v[110:113], v[146:149], v[186:189], v[110:113]
	v_mfma_f32_16x16x32_bf16 v[102:105], v[154:157], v[186:189], v[102:105]
	v_mfma_f32_16x16x32_bf16 v[94:97], v[146:149], v[200:203], v[94:97]
	v_mfma_f32_16x16x32_bf16 v[86:89], v[154:157], v[200:203], v[86:89]
	v_mfma_f32_16x16x32_bf16 v[78:81], v[146:149], v[208:211], v[78:81]
	v_mfma_f32_16x16x32_bf16 v[70:73], v[154:157], v[208:211], v[70:73]
	v_mfma_f32_16x16x32_bf16 v[126:129], v[150:153], v[182:185], v[126:129]
	v_mfma_f32_16x16x32_bf16 v[118:121], v[158:161], v[182:185], v[118:121]
	v_mfma_f32_16x16x32_bf16 v[110:113], v[150:153], v[190:193], v[110:113]
	v_mfma_f32_16x16x32_bf16 v[102:105], v[158:161], v[190:193], v[102:105]
	v_mfma_f32_16x16x32_bf16 v[94:97], v[150:153], v[204:207], v[94:97]
	v_mfma_f32_16x16x32_bf16 v[86:89], v[158:161], v[204:207], v[86:89]
	v_mfma_f32_16x16x32_bf16 v[78:81], v[150:153], v[212:215], v[78:81]
	v_mfma_f32_16x16x32_bf16 v[70:73], v[158:161], v[212:215], v[70:73]
	s_setprio 0
	s_setprio 1
	v_mfma_f32_16x16x32_bf16 v[122:125], v[162:165], v[178:181], v[122:125]
	v_mfma_f32_16x16x32_bf16 v[114:117], v[170:173], v[178:181], v[114:117]
	v_mfma_f32_16x16x32_bf16 v[106:109], v[162:165], v[186:189], v[106:109]
	v_mfma_f32_16x16x32_bf16 v[98:101], v[170:173], v[186:189], v[98:101]
	v_mfma_f32_16x16x32_bf16 v[90:93], v[162:165], v[200:203], v[90:93]
	v_mfma_f32_16x16x32_bf16 v[82:85], v[170:173], v[200:203], v[82:85]
	v_mfma_f32_16x16x32_bf16 v[74:77], v[162:165], v[208:211], v[74:77]
	v_mfma_f32_16x16x32_bf16 v[66:69], v[170:173], v[208:211], v[66:69]
	v_mfma_f32_16x16x32_bf16 v[122:125], v[166:169], v[182:185], v[122:125]
	v_mfma_f32_16x16x32_bf16 v[114:117], v[174:177], v[182:185], v[114:117]
	v_mfma_f32_16x16x32_bf16 v[106:109], v[166:169], v[190:193], v[106:109]
	v_mfma_f32_16x16x32_bf16 v[98:101], v[174:177], v[190:193], v[98:101]
	v_mfma_f32_16x16x32_bf16 v[90:93], v[166:169], v[204:207], v[90:93]
	v_mfma_f32_16x16x32_bf16 v[82:85], v[174:177], v[204:207], v[82:85]
	v_mfma_f32_16x16x32_bf16 v[74:77], v[166:169], v[212:215], v[74:77]
	v_mfma_f32_16x16x32_bf16 v[66:69], v[174:177], v[212:215], v[66:69]
	s_barrier
	s_setprio 0
	s_add_i32 s36, s38, s43
	v_lshl_add_u64 v[138:139], s[28:29], 0, v[132:133]
	s_mov_b32 m0, s36
	ds_read_b128 v[178:181], v144 offset:16384
	ds_read_b128 v[182:185], v144 offset:17408
	ds_read_b128 v[186:189], v144 offset:18432
	ds_read_b128 v[190:193], v144 offset:19456
	ds_read_b128 v[200:203], v144 offset:20480
	ds_read_b128 v[204:207], v144 offset:21504
	ds_read_b128 v[208:211], v144 offset:22528
	ds_read_b128 v[212:215], v144 offset:23552
	global_load_lds_dwordx4 v[138:139], off
	s_add_i32 m0, s36, 0x2000
	s_add_u32 s36, s28, 0x80000
	v_lshl_add_u64 v[220:221], s[28:29], 0, v[136:137]
	s_addc_u32 s37, s29, 0
	s_add_i32 s38, s39, s43
	global_load_lds_dwordx4 v[220:221], off
	v_lshl_add_u64 v[222:223], s[36:37], 0, v[132:133]
	s_mov_b32 m0, s38
	v_lshl_add_u64 v[230:231], s[30:31], 0, v[134:135]
	global_load_lds_dwordx4 v[222:223], off
	v_lshl_add_u64 v[222:223], s[36:37], 0, v[136:137]
	s_add_i32 m0, s38, 0x2000
	s_nop 0
	global_load_lds_dwordx4 v[222:223], off
	v_lshl_add_u64 v[222:223], s[30:31], 0, v[130:131]
	s_mov_b32 m0, s44
	s_nop 0
	global_load_lds_dwordx4 v[222:223], off
	s_mov_b32 m0, s45
	s_nop 0
	global_load_lds_dwordx4 v[230:231], off
	s_waitcnt vmcnt(8)
	s_waitcnt lgkmcnt(0)
	s_setprio 1
	s_barrier
; #define PG8_STAGE(bufoff, gbase, voff) do { _Pragma("unroll") for (int _i = 0; _i < 2; ++_i) \
;         __builtin_amdgcn_global_load_lds((const unsigned*)((const char*)(gbase) + (voff)[_i]), (PG8_LAS unsigned*)(lds + (bufoff) + ldsw + _i * 8192), 16, 0, PG8_AUX_##voff); } while (0)
; #define PG8_LDA(dst, b, h) do { _Pragma("unroll") for (int m = 0; m < 4; ++m) _Pragma("unroll") for (int k = 0; k < 2; ++k) dst[m][k] = *(const PG8_LAS bf16x8*)(lds + PG8_SA(b, h) + aoff + m * 2048 + k * 1024); } while (0)
; #define PG8_LDB(dst, b, h) do { _Pragma("unroll") for (int n = 0; n < 2; ++n) _Pragma("unroll") for (int k = 0; k < 2; ++k) dst[n][k] = *(const PG8_LAS bf16x8*)(lds + PG8_SB(b, h) + boff + n * 2048 + k * 1024); } while (0)
; #define PG8_MMA(ai, bj, At, Bt) do { __builtin_amdgcn_s_setprio(1); _Pragma("unroll") for (int m = 0; m < 4; ++m) _Pragma("unroll") for (int n = 0; n < 2; ++n) _Pragma("unroll") for (int k = 0; k < 2; ++k) \
;         acc[ai][bj][m][n] = __builtin_amdgcn_mfma_f32_16x16x32_bf16(Bt[n][k], At[m][k], acc[ai][bj][m][n], 0, 0, 0); __builtin_amdgcn_s_setprio(0); } while (0)
; #define PG8_WAIT_V(n) asm volatile("s_waitcnt vmcnt(" #n ")" ::: "memory")
; #define PG8_WAIT_L(n) asm volatile("s_waitcnt lgkmcnt(" #n ")" ::: "memory")
; #define PG8_BAR __builtin_amdgcn_s_barrier()
; #define PG8_SCHED __builtin_amdgcn_sched_barrier(0)
;     ...
;             PG8_LDB(B0, 0, 0); PG8_LDB(B1, 0, 1); PG8_SCHED; PG8_LDA(At, 0, 0); PG8_STAGE(PG8_SA(1, 1), a1 + hstep, voffA);
;             PG8_WAIT_V(8); PG8_WAIT_L(0); PG8_BAR; PG8_MMA(0, 0, At, B0); PG8_MMA(0, 1, At, B1); PG8_BAR; PG8_SCHED;
;             PG8_LDA(At, 0, 1); PG8_STAGE(PG8_SB(0, 0), b2, voffB); PG8_STAGE(PG8_SB(0, 1), b2 + hstep, voffB); PG8_STAGE(PG8_SA(0, 0), a2, voffA);
;             PG8_WAIT_V(8); PG8_WAIT_L(0); PG8_BAR; PG8_MMA(1, 0, At, B0); PG8_MMA(1, 1, At, B1); PG8_BAR; PG8_SCHED;
;             PG8_LDB(B0, 1, 0); PG8_LDB(B1, 1, 1); PG8_SCHED; PG8_LDA(At, 1, 0); PG8_STAGE(PG8_SA(0, 1), a2 + hstep, voffA);
;             PG8_WAIT_V(8); PG8_WAIT_L(0); PG8_BAR; PG8_MMA(0, 0, At, B0); PG8_MMA(0, 1, At, B1); PG8_BAR; PG8_SCHED;
;             PG8_LDA(At, 1, 1); PG8_STAGE(PG8_SB(1, 0), b3, voffB); PG8_STAGE(PG8_SB(1, 1), b3 + hstep, voffB); PG8_STAGE(PG8_SA(1, 0), a3, voffA);
;             PG8_WAIT_V(8); PG8_WAIT_L(0); PG8_BAR; PG8_MMA(1, 0, At, B0); PG8_MMA(1, 1, At, B1); PG8_BAR; PG8_SCHED;
	v_mfma_f32_16x16x32_bf16 v[62:65], v[146:149], v[178:181], v[62:65]
	v_mfma_f32_16x16x32_bf16 v[54:57], v[154:157], v[178:181], v[54:57]
	v_mfma_f32_16x16x32_bf16 v[46:49], v[146:149], v[186:189], v[46:49]
	v_mfma_f32_16x16x32_bf16 v[38:41], v[154:157], v[186:189], v[38:41]
	v_mfma_f32_16x16x32_bf16 v[30:33], v[146:149], v[200:203], v[30:33]
	v_mfma_f32_16x16x32_bf16 v[22:25], v[154:157], v[200:203], v[22:25]
	v_mfma_f32_16x16x32_bf16 v[14:17], v[146:149], v[208:211], v[14:17]
	v_mfma_f32_16x16x32_bf16 v[6:9], v[154:157], v[208:211], v[6:9]
	v_mfma_f32_16x16x32_bf16 v[62:65], v[150:153], v[182:185], v[62:65]
	v_mfma_f32_16x16x32_bf16 v[54:57], v[158:161], v[182:185], v[54:57]
	v_mfma_f32_16x16x32_bf16 v[46:49], v[150:153], v[190:193], v[46:49]
	v_mfma_f32_16x16x32_bf16 v[38:41], v[158:161], v[190:193], v[38:41]
	v_mfma_f32_16x16x32_bf16 v[30:33], v[150:153], v[204:207], v[30:33]
	v_mfma_f32_16x16x32_bf16 v[22:25], v[158:161], v[204:207], v[22:25]
	v_mfma_f32_16x16x32_bf16 v[14:17], v[150:153], v[212:215], v[14:17]
	v_mfma_f32_16x16x32_bf16 v[6:9], v[158:161], v[212:215], v[6:9]
	s_setprio 0
	s_setprio 1
	v_mfma_f32_16x16x32_bf16 v[58:61], v[162:165], v[178:181], v[58:61]
	v_mfma_f32_16x16x32_bf16 v[50:53], v[170:173], v[178:181], v[50:53]
	v_mfma_f32_16x16x32_bf16 v[42:45], v[162:165], v[186:189], v[42:45]
	v_mfma_f32_16x16x32_bf16 v[34:37], v[170:173], v[186:189], v[34:37]
	v_mfma_f32_16x16x32_bf16 v[26:29], v[162:165], v[200:203], v[26:29]
	v_mfma_f32_16x16x32_bf16 v[18:21], v[170:173], v[200:203], v[18:21]
	v_mfma_f32_16x16x32_bf16 v[10:13], v[162:165], v[208:211], v[10:13]
	v_mfma_f32_16x16x32_bf16 v[2:5], v[170:173], v[208:211], v[2:5]
	v_mfma_f32_16x16x32_bf16 v[58:61], v[166:169], v[182:185], v[58:61]
	v_mfma_f32_16x16x32_bf16 v[50:53], v[174:177], v[182:185], v[50:53]
	v_mfma_f32_16x16x32_bf16 v[42:45], v[166:169], v[190:193], v[42:45]
	v_mfma_f32_16x16x32_bf16 v[34:37], v[174:177], v[190:193], v[34:37]
	v_mfma_f32_16x16x32_bf16 v[26:29], v[166:169], v[204:207], v[26:29]
	v_mfma_f32_16x16x32_bf16 v[18:21], v[174:177], v[204:207], v[18:21]
	v_mfma_f32_16x16x32_bf16 v[10:13], v[166:169], v[212:215], v[10:13]
	v_mfma_f32_16x16x32_bf16 v[2:5], v[174:177], v[212:215], v[2:5]
	s_barrier
	s_setprio 0
	s_add_i32 s36, 0, 0x18000
	v_add_u32_e32 v145, s36, v142
	s_add_i32 s37, 0, 0x1c000
	ds_read_b128 v[146:149], v145
	ds_read_b128 v[150:153], v145 offset:1024
	ds_read_b128 v[154:157], v145 offset:2048
	ds_read_b128 v[158:161], v145 offset:3072
	v_add_u32_e32 v145, s37, v142
	ds_read_b128 v[162:165], v145
	ds_read_b128 v[166:169], v145 offset:1024
	ds_read_b128 v[170:173], v145 offset:2048
	ds_read_b128 v[174:177], v145 offset:3072
	s_add_u32 s30, s30, 0x80000
	s_addc_u32 s31, s31, 0
	s_mov_b32 m0, s46
	v_lshl_add_u64 v[232:233], s[30:31], 0, v[130:131]
	ds_read_b128 v[178:181], v144 offset:32768
	ds_read_b128 v[182:185], v144 offset:33792
	ds_read_b128 v[186:189], v144 offset:34816
	ds_read_b128 v[190:193], v144 offset:35840
	ds_read_b128 v[200:203], v144 offset:36864
	ds_read_b128 v[204:207], v144 offset:37888
	ds_read_b128 v[208:211], v144 offset:38912
	ds_read_b128 v[212:215], v144 offset:39936
	global_load_lds_dwordx4 v[232:233], off
	v_lshl_add_u64 v[232:233], s[30:31], 0, v[134:135]
	s_mov_b32 m0, s47
	s_nop 0
	global_load_lds_dwordx4 v[232:233], off
	s_waitcnt vmcnt(8)
	s_waitcnt lgkmcnt(0)
	s_setprio 1
	s_barrier
	v_mfma_f32_16x16x32_bf16 v[126:129], v[146:149], v[178:181], v[126:129]
	v_mfma_f32_16x16x32_bf16 v[118:121], v[154:157], v[178:181], v[118:121]
	v_mfma_f32_16x16x32_bf16 v[110:113], v[146:149], v[186:189], v[110:113]
	v_mfma_f32_16x16x32_bf16 v[102:105], v[154:157], v[186:189], v[102:105]
	v_mfma_f32_16x16x32_bf16 v[94:97], v[146:149], v[200:203], v[94:97]
	v_mfma_f32_16x16x32_bf16 v[86:89], v[154:157], v[200:203], v[86:89]
	v_mfma_f32_16x16x32_bf16 v[78:81], v[146:149], v[208:211], v[78:81]
	v_mfma_f32_16x16x32_bf16 v[70:73], v[154:157], v[208:211], v[70:73]
	v_mfma_f32_16x16x32_bf16 v[126:129], v[150:153], v[182:185], v[126:129]
	v_mfma_f32_16x16x32_bf16 v[118:121], v[158:161], v[182:185], v[118:121]
	v_mfma_f32_16x16x32_bf16 v[110:113], v[150:153], v[190:193], v[110:113]
	v_mfma_f32_16x16x32_bf16 v[102:105], v[158:161], v[190:193], v[102:105]
	v_mfma_f32_16x16x32_bf16 v[94:97], v[150:153], v[204:207], v[94:97]
	v_mfma_f32_16x16x32_bf16 v[86:89], v[158:161], v[204:207], v[86:89]
	v_mfma_f32_16x16x32_bf16 v[78:81], v[150:153], v[212:215], v[78:81]
	v_mfma_f32_16x16x32_bf16 v[70:73], v[158:161], v[212:215], v[70:73]
	s_setprio 0
	s_setprio 1
	v_mfma_f32_16x16x32_bf16 v[122:125], v[162:165], v[178:181], v[122:125]
	v_mfma_f32_16x16x32_bf16 v[114:117], v[170:173], v[178:181], v[114:117]
	v_mfma_f32_16x16x32_bf16 v[106:109], v[162:165], v[186:189], v[106:109]
	v_mfma_f32_16x16x32_bf16 v[98:101], v[170:173], v[186:189], v[98:101]
	v_mfma_f32_16x16x32_bf16 v[90:93], v[162:165], v[200:203], v[90:93]
	v_mfma_f32_16x16x32_bf16 v[82:85], v[170:173], v[200:203], v[82:85]
	v_mfma_f32_16x16x32_bf16 v[74:77], v[162:165], v[208:211], v[74:77]
	v_mfma_f32_16x16x32_bf16 v[66:69], v[170:173], v[208:211], v[66:69]
	v_mfma_f32_16x16x32_bf16 v[122:125], v[166:169], v[182:185], v[122:125]
	v_mfma_f32_16x16x32_bf16 v[114:117], v[174:177], v[182:185], v[114:117]
	v_mfma_f32_16x16x32_bf16 v[106:109], v[166:169], v[190:193], v[106:109]
	v_mfma_f32_16x16x32_bf16 v[98:101], v[174:177], v[190:193], v[98:101]
	v_mfma_f32_16x16x32_bf16 v[90:93], v[166:169], v[204:207], v[90:93]
	v_mfma_f32_16x16x32_bf16 v[82:85], v[174:177], v[204:207], v[82:85]
	v_mfma_f32_16x16x32_bf16 v[74:77], v[166:169], v[212:215], v[74:77]
	v_mfma_f32_16x16x32_bf16 v[66:69], v[174:177], v[212:215], v[66:69]
	s_barrier
; #define PG8_STAGE(bufoff, gbase, voff) do { _Pragma("unroll") for (int _i = 0; _i < 2; ++_i) \
;         __builtin_amdgcn_global_load_lds((const unsigned*)((const char*)(gbase) + (voff)[_i]), (PG8_LAS unsigned*)(lds + (bufoff) + ldsw + _i * 8192), 16, 0, PG8_AUX_##voff); } while (0)
; #define PG8_LDA(dst, b, h) do { _Pragma("unroll") for (int m = 0; m < 4; ++m) _Pragma("unroll") for (int k = 0; k < 2; ++k) dst[m][k] = *(const PG8_LAS bf16x8*)(lds + PG8_SA(b, h) + aoff + m * 2048 + k * 1024); } while (0)
; #define PG8_MMA(ai, bj, At, Bt) do { __builtin_amdgcn_s_setprio(1); _Pragma("unroll") for (int m = 0; m < 4; ++m) _Pragma("unroll") for (int n = 0; n < 2; ++n) _Pragma("unroll") for (int k = 0; k < 2; ++k) \
;         acc[ai][bj][m][n] = __builtin_amdgcn_mfma_f32_16x16x32_bf16(Bt[n][k], At[m][k], acc[ai][bj][m][n], 0, 0, 0); __builtin_amdgcn_s_setprio(0); } while (0)
; #define PG8_WAIT_V(n) asm volatile("s_waitcnt vmcnt(" #n ")" ::: "memory")
; #define PG8_WAIT_L(n) asm volatile("s_waitcnt lgkmcnt(" #n ")" ::: "memory")
; #define PG8_BAR __builtin_amdgcn_s_barrier()
; #define PG8_SCHED __builtin_amdgcn_sched_barrier(0)
;     ...
;         for (int t = 0; t < nt; t += 2) {
;             const bool last = (t == nt - 2);
;     ...
;             PG8_LDA(At, 1, 1); PG8_STAGE(PG8_SB(1, 0), b3, voffB); PG8_STAGE(PG8_SB(1, 1), b3 + hstep, voffB); PG8_STAGE(PG8_SA(1, 0), a3, voffA);
;             PG8_WAIT_V(8); PG8_WAIT_L(0); PG8_BAR; PG8_MMA(1, 0, At, B0); PG8_MMA(1, 1, At, B1); PG8_BAR; PG8_SCHED;
	s_setprio 0
	s_add_i32 s30, s36, s43
	v_lshl_add_u64 v[138:139], v[138:139], 0, s[2:3]
	s_mov_b32 m0, s30
	ds_read_b128 v[178:181], v144 offset:49152
	ds_read_b128 v[182:185], v144 offset:50176
	ds_read_b128 v[186:189], v144 offset:51200
	ds_read_b128 v[190:193], v144 offset:52224
	ds_read_b128 v[200:203], v144 offset:53248
	ds_read_b128 v[204:207], v144 offset:54272
	ds_read_b128 v[208:211], v144 offset:55296
	ds_read_b128 v[212:215], v144 offset:56320
	global_load_lds_dwordx4 v[138:139], off
	s_add_i32 m0, s30, 0x2000
	s_add_u32 s28, s28, 0x80080
	v_lshl_add_u64 v[138:139], v[220:221], 0, s[2:3]
	s_addc_u32 s29, s29, 0
	s_add_i32 s30, s37, s43
	global_load_lds_dwordx4 v[138:139], off
	v_lshl_add_u64 v[138:139], s[28:29], 0, v[132:133]
	s_mov_b32 m0, s30
	s_nop 0
	global_load_lds_dwordx4 v[138:139], off
	v_lshl_add_u64 v[138:139], s[28:29], 0, v[136:137]
	s_add_i32 m0, s30, 0x2000
	s_nop 0
	global_load_lds_dwordx4 v[138:139], off
	v_lshl_add_u64 v[138:139], v[222:223], 0, s[2:3]
	s_mov_b32 m0, s48
	s_nop 0
	global_load_lds_dwordx4 v[138:139], off
	v_lshl_add_u64 v[138:139], v[230:231], 0, s[2:3]
	s_mov_b32 m0, s49
	s_nop 0
	global_load_lds_dwordx4 v[138:139], off
	s_waitcnt vmcnt(8)
	s_waitcnt lgkmcnt(0)
	s_setprio 1
	s_barrier
	v_mfma_f32_16x16x32_bf16 v[62:65], v[146:149], v[178:181], v[62:65]
	v_mfma_f32_16x16x32_bf16 v[54:57], v[154:157], v[178:181], v[54:57]
	v_mfma_f32_16x16x32_bf16 v[46:49], v[146:149], v[186:189], v[46:49]
	v_mfma_f32_16x16x32_bf16 v[38:41], v[154:157], v[186:189], v[38:41]
	v_mfma_f32_16x16x32_bf16 v[30:33], v[146:149], v[200:203], v[30:33]
	v_mfma_f32_16x16x32_bf16 v[22:25], v[154:157], v[200:203], v[22:25]
	v_mfma_f32_16x16x32_bf16 v[14:17], v[146:149], v[208:211], v[14:17]
	v_mfma_f32_16x16x32_bf16 v[6:9], v[154:157], v[208:211], v[6:9]
	v_mfma_f32_16x16x32_bf16 v[62:65], v[150:153], v[182:185], v[62:65]
	v_mfma_f32_16x16x32_bf16 v[54:57], v[158:161], v[182:185], v[54:57]
	v_mfma_f32_16x16x32_bf16 v[46:49], v[150:153], v[190:193], v[46:49]
	v_mfma_f32_16x16x32_bf16 v[38:41], v[158:161], v[190:193], v[38:41]
	v_mfma_f32_16x16x32_bf16 v[30:33], v[150:153], v[204:207], v[30:33]
	v_mfma_f32_16x16x32_bf16 v[22:25], v[158:161], v[204:207], v[22:25]
	v_mfma_f32_16x16x32_bf16 v[14:17], v[150:153], v[212:215], v[14:17]
	v_mfma_f32_16x16x32_bf16 v[6:9], v[158:161], v[212:215], v[6:9]
	s_setprio 0
	s_setprio 1
	v_mfma_f32_16x16x32_bf16 v[58:61], v[162:165], v[178:181], v[58:61]
	v_mfma_f32_16x16x32_bf16 v[50:53], v[170:173], v[178:181], v[50:53]
	v_mfma_f32_16x16x32_bf16 v[42:45], v[162:165], v[186:189], v[42:45]
	v_mfma_f32_16x16x32_bf16 v[34:37], v[170:173], v[186:189], v[34:37]
	v_mfma_f32_16x16x32_bf16 v[26:29], v[162:165], v[200:203], v[26:29]
	v_mfma_f32_16x16x32_bf16 v[18:21], v[170:173], v[200:203], v[18:21]
	v_mfma_f32_16x16x32_bf16 v[10:13], v[162:165], v[208:211], v[10:13]
	v_mfma_f32_16x16x32_bf16 v[2:5], v[170:173], v[208:211], v[2:5]
	v_mfma_f32_16x16x32_bf16 v[58:61], v[166:169], v[182:185], v[58:61]
	v_mfma_f32_16x16x32_bf16 v[50:53], v[174:177], v[182:185], v[50:53]
	v_mfma_f32_16x16x32_bf16 v[42:45], v[166:169], v[190:193], v[42:45]
	v_mfma_f32_16x16x32_bf16 v[34:37], v[174:177], v[190:193], v[34:37]
	v_mfma_f32_16x16x32_bf16 v[26:29], v[166:169], v[204:207], v[26:29]
	v_mfma_f32_16x16x32_bf16 v[18:21], v[174:177], v[204:207], v[18:21]
	v_mfma_f32_16x16x32_bf16 v[10:13], v[166:169], v[212:215], v[10:13]
	v_mfma_f32_16x16x32_bf16 v[2:5], v[174:177], v[212:215], v[2:5]
	s_barrier
	s_setprio 0
	s_cmp_gt_u32 s56, 29
	s_cbranch_scc1 .LBB0_584
	s_mov_b32 s56, s35
	s_branch .LBB0_565

; #define PG8_STAGE(bufoff, gbase, voff) do { _Pragma("unroll") for (int _i = 0; _i < 2; ++_i) \
;         __builtin_amdgcn_global_load_lds((const unsigned*)((const char*)(gbase) + (voff)[_i]), (PG8_LAS unsigned*)(lds + (bufoff) + ldsw + _i * 8192), 16, 0, PG8_AUX_##voff); } while (0)
; #define PG8_LDA(dst, b, h) do { _Pragma("unroll") for (int m = 0; m < 4; ++m) _Pragma("unroll") for (int k = 0; k < 2; ++k) dst[m][k] = *(const PG8_LAS bf16x8*)(lds + PG8_SA(b, h) + aoff + m * 2048 + k * 1024); } while (0)
; #define PG8_LDB(dst, b, h) do { _Pragma("unroll") for (int n = 0; n < 2; ++n) _Pragma("unroll") for (int k = 0; k < 2; ++k) dst[n][k] = *(const PG8_LAS bf16x8*)(lds + PG8_SB(b, h) + boff + n * 2048 + k * 1024); } while (0)
; #define PG8_WAIT_V(n) asm volatile("s_waitcnt vmcnt(" #n ")" ::: "memory")
; #define PG8_WAIT_L(n) asm volatile("s_waitcnt lgkmcnt(" #n ")" ::: "memory")
;     ...
;         for (int t = 0; t < nt; t += 2) {
;             const bool last = (t == nt - 2);
;             const char* a1 = cA + (size_t)(t + 1) * kstep;
;             const char* a2 = last ? nA : cA + (size_t)(t + 2) * kstep; const char* b2 = last ? nB : cB + (size_t)(t + 2) * kstep;
;             const char* a3 = a2 + kstep; const char* b3 = b2 + kstep;
;             if (last && has_next) S.a_ready(nxt);
;             if constexpr (SP2) {
;             PG8_LDB(B0, 0, 0); PG8_LDB(B1, 0, 1); PG8_SCHED; PG8_LDA(At, 0, 0); PG8_STAGE(PG8_SA(1, 1), a1 + hstep, voffA);
;             PG8_WAIT_V(8); PG8_WAIT_L(0); PG8_BAR; PG8_MMA(0, 0, At, B0); PG8_MMA(0, 1, At, B1); PG8_BAR; PG8_SCHED;
;             PG8_LDA(At, 0, 1); PG8_STAGE(PG8_SB(0, 0), b2, voffB); PG8_STAGE(PG8_SB(0, 1), b2 + hstep, voffB); PG8_STAGE(PG8_SA(0, 0), a2, voffA);
;             PG8_WAIT_V(8); PG8_WAIT_L(0); PG8_BAR; PG8_MMA(1, 0, At, B0); PG8_MMA(1, 1, At, B1); PG8_BAR; PG8_SCHED;
;             PG8_LDB(B0, 1, 0); PG8_LDB(B1, 1, 1); PG8_SCHED; PG8_LDA(At, 1, 0); PG8_STAGE(PG8_SA(0, 1), a2 + hstep, voffA);
;             PG8_WAIT_V(8); PG8_WAIT_L(0); PG8_BAR; PG8_MMA(0, 0, At, B0); PG8_MMA(0, 1, At, B1); PG8_BAR; PG8_SCHED;
;             PG8_LDA(At, 1, 1); PG8_STAGE(PG8_SB(1, 0), b3, voffB); PG8_STAGE(PG8_SB(1, 1), b3 + hstep, voffB); PG8_STAGE(PG8_SA(1, 0), a3, voffA);
;             PG8_WAIT_V(8); PG8_WAIT_L(0); PG8_BAR; PG8_MMA(1, 0, At, B0); PG8_MMA(1, 1, At, B1); PG8_BAR; PG8_SCHED;
.LBB0_809:
	s_add_u32 s26, s22, s24
	s_addc_u32 s27, s23, s25
	s_add_u32 s53, s20, s24
	s_addc_u32 s54, s21, s25
	s_add_i32 s55, 0, 0x10000
	s_cmp_eq_u32 s11, s17
	s_cselect_b32 s29, s5, s27
	s_cselect_b32 s28, s4, s26
	s_cselect_b32 s27, s19, s54
	s_cselect_b32 s26, s18, s53
	s_add_i32 s53, 0, 0x14000
	v_add_u32_e32 v162, s55, v146
	v_add_u32_e32 v178, s53, v146
	ds_read_b128 v[150:153], v162
	ds_read_b128 v[154:157], v162 offset:1024
	ds_read_b128 v[158:161], v162 offset:2048
	ds_read_b128 v[162:165], v162 offset:3072
	ds_read_b128 v[166:169], v178
	ds_read_b128 v[170:173], v178 offset:1024
	ds_read_b128 v[174:177], v178 offset:2048
	ds_read_b128 v[178:181], v178 offset:3072
	v_lshl_add_u64 v[214:215], s[22:23], 0, v[142:143]
	s_add_i32 m0, s40, 0xc000
	ds_read_b128 v[182:185], v149
	ds_read_b128 v[186:189], v149 offset:1024
	ds_read_b128 v[190:193], v149 offset:2048
	ds_read_b128 v[200:203], v149 offset:3072
	ds_read_b128 v[204:207], v149 offset:4096
	ds_read_b128 v[208:211], v149 offset:5120
	ds_read_b128 v[232:235], v149 offset:6144
	ds_read_b128 v[236:239], v149 offset:7168
	global_load_lds_dwordx4 v[214:215], off
	v_lshl_add_u64 v[214:215], s[22:23], 0, v[140:141]
	s_add_i32 m0, s40, 0xe000
	s_nop 0
	global_load_lds_dwordx4 v[214:215], off
	s_waitcnt vmcnt(8)
	s_waitcnt lgkmcnt(0)
	s_setprio 1
	s_barrier
	v_mfma_f32_16x16x32_bf16 v[98:101], v[150:153], v[182:185], v[98:101]
	v_mfma_f32_16x16x32_bf16 v[102:105], v[158:161], v[182:185], v[102:105]
	v_mfma_f32_16x16x32_bf16 v[126:129], v[150:153], v[190:193], v[126:129]
	v_mfma_f32_16x16x32_bf16 v[122:125], v[158:161], v[190:193], v[122:125]
	v_mfma_f32_16x16x32_bf16 v[94:97], v[150:153], v[204:207], v[94:97]
	v_mfma_f32_16x16x32_bf16 v[90:93], v[158:161], v[204:207], v[90:93]
	v_mfma_f32_16x16x32_bf16 v[78:81], v[150:153], v[232:235], v[78:81]
	v_mfma_f32_16x16x32_bf16 v[74:77], v[158:161], v[232:235], v[74:77]
	v_mfma_f32_16x16x32_bf16 v[98:101], v[154:157], v[186:189], v[98:101]
	v_mfma_f32_16x16x32_bf16 v[102:105], v[162:165], v[186:189], v[102:105]
	v_mfma_f32_16x16x32_bf16 v[126:129], v[154:157], v[200:203], v[126:129]
	v_mfma_f32_16x16x32_bf16 v[122:125], v[162:165], v[200:203], v[122:125]
	v_mfma_f32_16x16x32_bf16 v[94:97], v[154:157], v[208:211], v[94:97]
	v_mfma_f32_16x16x32_bf16 v[90:93], v[162:165], v[208:211], v[90:93]
	v_mfma_f32_16x16x32_bf16 v[78:81], v[154:157], v[236:239], v[78:81]
	v_mfma_f32_16x16x32_bf16 v[74:77], v[162:165], v[236:239], v[74:77]
	s_setprio 0
	s_setprio 1
	v_mfma_f32_16x16x32_bf16 v[106:109], v[166:169], v[182:185], v[106:109]
	v_mfma_f32_16x16x32_bf16 v[110:113], v[174:177], v[182:185], v[110:113]
	v_mfma_f32_16x16x32_bf16 v[114:117], v[166:169], v[190:193], v[114:117]
	v_mfma_f32_16x16x32_bf16 v[118:121], v[174:177], v[190:193], v[118:121]
	v_mfma_f32_16x16x32_bf16 v[86:89], v[166:169], v[204:207], v[86:89]
	v_mfma_f32_16x16x32_bf16 v[82:85], v[174:177], v[204:207], v[82:85]
	v_mfma_f32_16x16x32_bf16 v[70:73], v[166:169], v[232:235], v[70:73]
	v_mfma_f32_16x16x32_bf16 v[66:69], v[174:177], v[232:235], v[66:69]
	v_mfma_f32_16x16x32_bf16 v[106:109], v[170:173], v[186:189], v[106:109]
	v_mfma_f32_16x16x32_bf16 v[110:113], v[178:181], v[186:189], v[110:113]
	v_mfma_f32_16x16x32_bf16 v[114:117], v[170:173], v[200:203], v[114:117]
	v_mfma_f32_16x16x32_bf16 v[118:121], v[178:181], v[200:203], v[118:121]
	v_mfma_f32_16x16x32_bf16 v[86:89], v[170:173], v[208:211], v[86:89]
	v_mfma_f32_16x16x32_bf16 v[82:85], v[178:181], v[208:211], v[82:85]
	v_mfma_f32_16x16x32_bf16 v[70:73], v[170:173], v[236:239], v[70:73]
	v_mfma_f32_16x16x32_bf16 v[66:69], v[178:181], v[236:239], v[66:69]
	s_barrier
	s_setprio 0
	s_add_i32 s54, s55, s39
	v_lshl_add_u64 v[214:215], s[26:27], 0, v[194:195]
	s_mov_b32 m0, s54
	ds_read_b128 v[182:185], v149 offset:16384
	ds_read_b128 v[186:189], v149 offset:17408
	ds_read_b128 v[190:193], v149 offset:18432
	ds_read_b128 v[200:203], v149 offset:19456
	ds_read_b128 v[204:207], v149 offset:20480
	ds_read_b128 v[208:211], v149 offset:21504
	ds_read_b128 v[232:235], v149 offset:22528
	ds_read_b128 v[236:239], v149 offset:23552
	global_load_lds_dwordx4 v[214:215], off
	s_add_i32 m0, s54, 0x2000
	s_add_u32 s54, s26, 0x160000
	v_lshl_add_u64 v[220:221], s[26:27], 0, v[134:135]
	s_addc_u32 s55, s27, 0
	s_add_i32 s53, s53, s39
	global_load_lds_dwordx4 v[220:221], off
	v_lshl_add_u64 v[222:223], s[54:55], 0, v[194:195]
	s_mov_b32 m0, s53
	v_lshl_add_u64 v[240:241], s[28:29], 0, v[132:133]
	global_load_lds_dwordx4 v[222:223], off
	v_lshl_add_u64 v[222:223], s[54:55], 0, v[134:135]
	s_add_i32 m0, s53, 0x2000
	s_nop 0
	global_load_lds_dwordx4 v[222:223], off
	v_lshl_add_u64 v[222:223], s[28:29], 0, v[130:131]
	s_mov_b32 m0, s40
	s_nop 0
	global_load_lds_dwordx4 v[222:223], off
	s_mov_b32 m0, s42
	s_nop 0
	global_load_lds_dwordx4 v[240:241], off
	s_waitcnt vmcnt(8)
	s_waitcnt lgkmcnt(0)
	s_setprio 1
	s_barrier
; #define PG8_STAGE(bufoff, gbase, voff) do { _Pragma("unroll") for (int _i = 0; _i < 2; ++_i) \
;         __builtin_amdgcn_global_load_lds((const unsigned*)((const char*)(gbase) + (voff)[_i]), (PG8_LAS unsigned*)(lds + (bufoff) + ldsw + _i * 8192), 16, 0, PG8_AUX_##voff); } while (0)
; #define PG8_LDA(dst, b, h) do { _Pragma("unroll") for (int m = 0; m < 4; ++m) _Pragma("unroll") for (int k = 0; k < 2; ++k) dst[m][k] = *(const PG8_LAS bf16x8*)(lds + PG8_SA(b, h) + aoff + m * 2048 + k * 1024); } while (0)
; #define PG8_LDB(dst, b, h) do { _Pragma("unroll") for (int n = 0; n < 2; ++n) _Pragma("unroll") for (int k = 0; k < 2; ++k) dst[n][k] = *(const PG8_LAS bf16x8*)(lds + PG8_SB(b, h) + boff + n * 2048 + k * 1024); } while (0)
; #define PG8_MMA(ai, bj, At, Bt) do { __builtin_amdgcn_s_setprio(1); _Pragma("unroll") for (int m = 0; m < 4; ++m) _Pragma("unroll") for (int n = 0; n < 2; ++n) _Pragma("unroll") for (int k = 0; k < 2; ++k) \
;         acc[ai][bj][m][n] = __builtin_amdgcn_mfma_f32_16x16x32_bf16(Bt[n][k], At[m][k], acc[ai][bj][m][n], 0, 0, 0); __builtin_amdgcn_s_setprio(0); } while (0)
; #define PG8_WAIT_V(n) asm volatile("s_waitcnt vmcnt(" #n ")" ::: "memory")
; #define PG8_WAIT_L(n) asm volatile("s_waitcnt lgkmcnt(" #n ")" ::: "memory")
; #define PG8_BAR __builtin_amdgcn_s_barrier()
; #define PG8_SCHED __builtin_amdgcn_sched_barrier(0)
;     ...
;             PG8_LDA(At, 0, 1); PG8_STAGE(PG8_SB(0, 0), b2, voffB); PG8_STAGE(PG8_SB(0, 1), b2 + hstep, voffB); PG8_STAGE(PG8_SA(0, 0), a2, voffA);
;             PG8_WAIT_V(8); PG8_WAIT_L(0); PG8_BAR; PG8_MMA(1, 0, At, B0); PG8_MMA(1, 1, At, B1); PG8_BAR; PG8_SCHED;
;             PG8_LDB(B0, 1, 0); PG8_LDB(B1, 1, 1); PG8_SCHED; PG8_LDA(At, 1, 0); PG8_STAGE(PG8_SA(0, 1), a2 + hstep, voffA);
;             PG8_WAIT_V(8); PG8_WAIT_L(0); PG8_BAR; PG8_MMA(0, 0, At, B0); PG8_MMA(0, 1, At, B1); PG8_BAR; PG8_SCHED;
	v_mfma_f32_16x16x32_bf16 v[62:65], v[150:153], v[182:185], v[62:65]
	v_mfma_f32_16x16x32_bf16 v[58:61], v[158:161], v[182:185], v[58:61]
	v_mfma_f32_16x16x32_bf16 v[46:49], v[150:153], v[190:193], v[46:49]
	v_mfma_f32_16x16x32_bf16 v[42:45], v[158:161], v[190:193], v[42:45]
	v_mfma_f32_16x16x32_bf16 v[30:33], v[150:153], v[204:207], v[30:33]
	v_mfma_f32_16x16x32_bf16 v[26:29], v[158:161], v[204:207], v[26:29]
	v_mfma_f32_16x16x32_bf16 v[14:17], v[150:153], v[232:235], v[14:17]
	v_mfma_f32_16x16x32_bf16 v[10:13], v[158:161], v[232:235], v[10:13]
	v_mfma_f32_16x16x32_bf16 v[62:65], v[154:157], v[186:189], v[62:65]
	v_mfma_f32_16x16x32_bf16 v[58:61], v[162:165], v[186:189], v[58:61]
	v_mfma_f32_16x16x32_bf16 v[46:49], v[154:157], v[200:203], v[46:49]
	v_mfma_f32_16x16x32_bf16 v[42:45], v[162:165], v[200:203], v[42:45]
	v_mfma_f32_16x16x32_bf16 v[30:33], v[154:157], v[208:211], v[30:33]
	v_mfma_f32_16x16x32_bf16 v[26:29], v[162:165], v[208:211], v[26:29]
	v_mfma_f32_16x16x32_bf16 v[14:17], v[154:157], v[236:239], v[14:17]
	v_mfma_f32_16x16x32_bf16 v[10:13], v[162:165], v[236:239], v[10:13]
	s_setprio 0
	s_setprio 1
	v_mfma_f32_16x16x32_bf16 v[54:57], v[166:169], v[182:185], v[54:57]
	v_mfma_f32_16x16x32_bf16 v[50:53], v[174:177], v[182:185], v[50:53]
	v_mfma_f32_16x16x32_bf16 v[38:41], v[166:169], v[190:193], v[38:41]
	v_mfma_f32_16x16x32_bf16 v[34:37], v[174:177], v[190:193], v[34:37]
	v_mfma_f32_16x16x32_bf16 v[22:25], v[166:169], v[204:207], v[22:25]
	v_mfma_f32_16x16x32_bf16 v[18:21], v[174:177], v[204:207], v[18:21]
	v_mfma_f32_16x16x32_bf16 v[6:9], v[166:169], v[232:235], v[6:9]
	v_mfma_f32_16x16x32_bf16 v[2:5], v[174:177], v[232:235], v[2:5]
	v_mfma_f32_16x16x32_bf16 v[54:57], v[170:173], v[186:189], v[54:57]
	v_mfma_f32_16x16x32_bf16 v[50:53], v[178:181], v[186:189], v[50:53]
	v_mfma_f32_16x16x32_bf16 v[38:41], v[170:173], v[200:203], v[38:41]
	v_mfma_f32_16x16x32_bf16 v[34:37], v[178:181], v[200:203], v[34:37]
	v_mfma_f32_16x16x32_bf16 v[22:25], v[170:173], v[208:211], v[22:25]
	v_mfma_f32_16x16x32_bf16 v[18:21], v[178:181], v[208:211], v[18:21]
	v_mfma_f32_16x16x32_bf16 v[6:9], v[170:173], v[236:239], v[6:9]
	v_mfma_f32_16x16x32_bf16 v[2:5], v[178:181], v[236:239], v[2:5]
	s_barrier
	s_setprio 0
	s_add_i32 s53, 0, 0x18000
	s_add_i32 s54, 0, 0x1c000
	v_add_u32_e32 v162, s53, v146
	v_add_u32_e32 v178, s54, v146
	ds_read_b128 v[150:153], v162
	ds_read_b128 v[154:157], v162 offset:1024
	ds_read_b128 v[158:161], v162 offset:2048
	ds_read_b128 v[162:165], v162 offset:3072
	ds_read_b128 v[166:169], v178
	ds_read_b128 v[170:173], v178 offset:1024
	ds_read_b128 v[174:177], v178 offset:2048
	ds_read_b128 v[178:181], v178 offset:3072
	s_add_u32 s28, s28, 0x160000
	s_addc_u32 s29, s29, 0
	s_mov_b32 m0, s43
	v_lshl_add_u64 v[242:243], s[28:29], 0, v[130:131]
	ds_read_b128 v[182:185], v149 offset:32768
	ds_read_b128 v[186:189], v149 offset:33792
	ds_read_b128 v[190:193], v149 offset:34816
	ds_read_b128 v[200:203], v149 offset:35840
	ds_read_b128 v[204:207], v149 offset:36864
	ds_read_b128 v[208:211], v149 offset:37888
	ds_read_b128 v[232:235], v149 offset:38912
	ds_read_b128 v[236:239], v149 offset:39936
	global_load_lds_dwordx4 v[242:243], off
	v_lshl_add_u64 v[242:243], s[28:29], 0, v[132:133]
	s_mov_b32 m0, s44
	s_nop 0
	global_load_lds_dwordx4 v[242:243], off
	s_waitcnt vmcnt(8)
	s_waitcnt lgkmcnt(0)
	s_setprio 1
	s_barrier
	v_mfma_f32_16x16x32_bf16 v[98:101], v[150:153], v[182:185], v[98:101]
	v_mfma_f32_16x16x32_bf16 v[102:105], v[158:161], v[182:185], v[102:105]
	v_mfma_f32_16x16x32_bf16 v[126:129], v[150:153], v[190:193], v[126:129]
	v_mfma_f32_16x16x32_bf16 v[122:125], v[158:161], v[190:193], v[122:125]
	v_mfma_f32_16x16x32_bf16 v[94:97], v[150:153], v[204:207], v[94:97]
	v_mfma_f32_16x16x32_bf16 v[90:93], v[158:161], v[204:207], v[90:93]
	v_mfma_f32_16x16x32_bf16 v[78:81], v[150:153], v[232:235], v[78:81]
	v_mfma_f32_16x16x32_bf16 v[74:77], v[158:161], v[232:235], v[74:77]
	v_mfma_f32_16x16x32_bf16 v[98:101], v[154:157], v[186:189], v[98:101]
	v_mfma_f32_16x16x32_bf16 v[102:105], v[162:165], v[186:189], v[102:105]
	v_mfma_f32_16x16x32_bf16 v[126:129], v[154:157], v[200:203], v[126:129]
	v_mfma_f32_16x16x32_bf16 v[122:125], v[162:165], v[200:203], v[122:125]
	v_mfma_f32_16x16x32_bf16 v[94:97], v[154:157], v[208:211], v[94:97]
	v_mfma_f32_16x16x32_bf16 v[90:93], v[162:165], v[208:211], v[90:93]
	v_mfma_f32_16x16x32_bf16 v[78:81], v[154:157], v[236:239], v[78:81]
	v_mfma_f32_16x16x32_bf16 v[74:77], v[162:165], v[236:239], v[74:77]
	s_setprio 0
	s_setprio 1
	v_mfma_f32_16x16x32_bf16 v[106:109], v[166:169], v[182:185], v[106:109]
	v_mfma_f32_16x16x32_bf16 v[110:113], v[174:177], v[182:185], v[110:113]
	v_mfma_f32_16x16x32_bf16 v[114:117], v[166:169], v[190:193], v[114:117]
	v_mfma_f32_16x16x32_bf16 v[118:121], v[174:177], v[190:193], v[118:121]
	v_mfma_f32_16x16x32_bf16 v[86:89], v[166:169], v[204:207], v[86:89]
	v_mfma_f32_16x16x32_bf16 v[82:85], v[174:177], v[204:207], v[82:85]
	v_mfma_f32_16x16x32_bf16 v[70:73], v[166:169], v[232:235], v[70:73]
	v_mfma_f32_16x16x32_bf16 v[66:69], v[174:177], v[232:235], v[66:69]
	v_mfma_f32_16x16x32_bf16 v[106:109], v[170:173], v[186:189], v[106:109]
	v_mfma_f32_16x16x32_bf16 v[110:113], v[178:181], v[186:189], v[110:113]
	v_mfma_f32_16x16x32_bf16 v[114:117], v[170:173], v[200:203], v[114:117]
	v_mfma_f32_16x16x32_bf16 v[118:121], v[178:181], v[200:203], v[118:121]
	v_mfma_f32_16x16x32_bf16 v[86:89], v[170:173], v[208:211], v[86:89]
	v_mfma_f32_16x16x32_bf16 v[82:85], v[178:181], v[208:211], v[82:85]
	v_mfma_f32_16x16x32_bf16 v[70:73], v[170:173], v[236:239], v[70:73]
	v_mfma_f32_16x16x32_bf16 v[66:69], v[178:181], v[236:239], v[66:69]
	s_barrier
; #define PG8_STAGE(bufoff, gbase, voff) do { _Pragma("unroll") for (int _i = 0; _i < 2; ++_i) \
;         __builtin_amdgcn_global_load_lds((const unsigned*)((const char*)(gbase) + (voff)[_i]), (PG8_LAS unsigned*)(lds + (bufoff) + ldsw + _i * 8192), 16, 0, PG8_AUX_##voff); } while (0)
; #define PG8_LDA(dst, b, h) do { _Pragma("unroll") for (int m = 0; m < 4; ++m) _Pragma("unroll") for (int k = 0; k < 2; ++k) dst[m][k] = *(const PG8_LAS bf16x8*)(lds + PG8_SA(b, h) + aoff + m * 2048 + k * 1024); } while (0)
; #define PG8_MMA(ai, bj, At, Bt) do { __builtin_amdgcn_s_setprio(1); _Pragma("unroll") for (int m = 0; m < 4; ++m) _Pragma("unroll") for (int n = 0; n < 2; ++n) _Pragma("unroll") for (int k = 0; k < 2; ++k) \
;         acc[ai][bj][m][n] = __builtin_amdgcn_mfma_f32_16x16x32_bf16(Bt[n][k], At[m][k], acc[ai][bj][m][n], 0, 0, 0); __builtin_amdgcn_s_setprio(0); } while (0)
; #define PG8_WAIT_V(n) asm volatile("s_waitcnt vmcnt(" #n ")" ::: "memory")
; #define PG8_WAIT_L(n) asm volatile("s_waitcnt lgkmcnt(" #n ")" ::: "memory")
; #define PG8_BAR __builtin_amdgcn_s_barrier()
; #define PG8_SCHED __builtin_amdgcn_sched_barrier(0)
;     ...
;         for (int t = 0; t < nt; t += 2) {
;             const bool last = (t == nt - 2);
;     ...
;             PG8_LDA(At, 1, 1); PG8_STAGE(PG8_SB(1, 0), b3, voffB); PG8_STAGE(PG8_SB(1, 1), b3 + hstep, voffB); PG8_STAGE(PG8_SA(1, 0), a3, voffA);
;             PG8_WAIT_V(8); PG8_WAIT_L(0); PG8_BAR; PG8_MMA(1, 0, At, B0); PG8_MMA(1, 1, At, B1); PG8_BAR; PG8_SCHED;
;     ...
;         if constexpr (ALIGN_EPI) { if (wr == 0) PG8_BAR; }
	s_setprio 0
	s_add_i32 s28, s53, s39
	v_lshl_add_u64 v[214:215], v[214:215], 0, s[2:3]
	s_mov_b32 m0, s28
	ds_read_b128 v[182:185], v149 offset:49152
	ds_read_b128 v[186:189], v149 offset:50176
	ds_read_b128 v[190:193], v149 offset:51200
	ds_read_b128 v[200:203], v149 offset:52224
	ds_read_b128 v[204:207], v149 offset:53248
	ds_read_b128 v[208:211], v149 offset:54272
	ds_read_b128 v[232:235], v149 offset:55296
	ds_read_b128 v[236:239], v149 offset:56320
	global_load_lds_dwordx4 v[214:215], off
	s_add_i32 m0, s28, 0x2000
	s_add_u32 s26, s26, 0x160080
	v_lshl_add_u64 v[214:215], v[220:221], 0, s[2:3]
	s_addc_u32 s27, s27, 0
	s_add_i32 s28, s54, s39
	global_load_lds_dwordx4 v[214:215], off
	v_lshl_add_u64 v[214:215], s[26:27], 0, v[194:195]
	s_mov_b32 m0, s28
	s_nop 0
	global_load_lds_dwordx4 v[214:215], off
	v_lshl_add_u64 v[214:215], s[26:27], 0, v[134:135]
	s_add_i32 m0, s28, 0x2000
	s_nop 0
	global_load_lds_dwordx4 v[214:215], off
	v_lshl_add_u64 v[214:215], v[222:223], 0, s[2:3]
	s_mov_b32 m0, s45
	s_nop 0
	global_load_lds_dwordx4 v[214:215], off
	v_lshl_add_u64 v[214:215], v[240:241], 0, s[2:3]
	s_mov_b32 m0, s46
	s_nop 0
	global_load_lds_dwordx4 v[214:215], off
	s_waitcnt vmcnt(8)
	s_waitcnt lgkmcnt(0)
	s_setprio 1
	s_barrier
	v_mfma_f32_16x16x32_bf16 v[62:65], v[150:153], v[182:185], v[62:65]
	v_mfma_f32_16x16x32_bf16 v[58:61], v[158:161], v[182:185], v[58:61]
	v_mfma_f32_16x16x32_bf16 v[46:49], v[150:153], v[190:193], v[46:49]
	v_mfma_f32_16x16x32_bf16 v[42:45], v[158:161], v[190:193], v[42:45]
	v_mfma_f32_16x16x32_bf16 v[30:33], v[150:153], v[204:207], v[30:33]
	v_mfma_f32_16x16x32_bf16 v[26:29], v[158:161], v[204:207], v[26:29]
	v_mfma_f32_16x16x32_bf16 v[14:17], v[150:153], v[232:235], v[14:17]
	v_mfma_f32_16x16x32_bf16 v[10:13], v[158:161], v[232:235], v[10:13]
	v_mfma_f32_16x16x32_bf16 v[62:65], v[154:157], v[186:189], v[62:65]
	v_mfma_f32_16x16x32_bf16 v[58:61], v[162:165], v[186:189], v[58:61]
	v_mfma_f32_16x16x32_bf16 v[46:49], v[154:157], v[200:203], v[46:49]
	v_mfma_f32_16x16x32_bf16 v[42:45], v[162:165], v[200:203], v[42:45]
	v_mfma_f32_16x16x32_bf16 v[30:33], v[154:157], v[208:211], v[30:33]
	v_mfma_f32_16x16x32_bf16 v[26:29], v[162:165], v[208:211], v[26:29]
	v_mfma_f32_16x16x32_bf16 v[14:17], v[154:157], v[236:239], v[14:17]
	v_mfma_f32_16x16x32_bf16 v[10:13], v[162:165], v[236:239], v[10:13]
	s_setprio 0
	s_setprio 1
	v_mfma_f32_16x16x32_bf16 v[54:57], v[166:169], v[182:185], v[54:57]
	v_mfma_f32_16x16x32_bf16 v[50:53], v[174:177], v[182:185], v[50:53]
	v_mfma_f32_16x16x32_bf16 v[38:41], v[166:169], v[190:193], v[38:41]
	v_mfma_f32_16x16x32_bf16 v[34:37], v[174:177], v[190:193], v[34:37]
	v_mfma_f32_16x16x32_bf16 v[22:25], v[166:169], v[204:207], v[22:25]
	v_mfma_f32_16x16x32_bf16 v[18:21], v[174:177], v[204:207], v[18:21]
	v_mfma_f32_16x16x32_bf16 v[6:9], v[166:169], v[232:235], v[6:9]
	v_mfma_f32_16x16x32_bf16 v[2:5], v[174:177], v[232:235], v[2:5]
	v_mfma_f32_16x16x32_bf16 v[54:57], v[170:173], v[186:189], v[54:57]
	v_mfma_f32_16x16x32_bf16 v[50:53], v[178:181], v[186:189], v[50:53]
	v_mfma_f32_16x16x32_bf16 v[38:41], v[170:173], v[200:203], v[38:41]
	v_mfma_f32_16x16x32_bf16 v[34:37], v[178:181], v[200:203], v[34:37]
	v_mfma_f32_16x16x32_bf16 v[22:25], v[170:173], v[208:211], v[22:25]
	v_mfma_f32_16x16x32_bf16 v[18:21], v[178:181], v[208:211], v[18:21]
	v_mfma_f32_16x16x32_bf16 v[6:9], v[170:173], v[236:239], v[6:9]
	v_mfma_f32_16x16x32_bf16 v[2:5], v[178:181], v[236:239], v[2:5]
	s_barrier
	s_setprio 0
	s_add_i32 s26, s17, 2
	s_add_u32 s24, s24, 0x100
	s_addc_u32 s25, s25, 0
	v_lshl_add_u64 v[142:143], v[142:143], 0, s[56:57]
	v_lshl_add_u64 v[140:141], v[140:141], 0, s[56:57]
	s_cmp_ge_i32 s17, s11
	s_mov_b32 s17, s26
	s_cbranch_scc0 .LBB0_809
	s_and_b64 vcc, exec, s[14:15]
	s_cbranch_vccz .LBB0_812
	s_barrier

; #define PG8_STAGE(bufoff, gbase, voff) do { _Pragma("unroll") for (int _i = 0; _i < 2; ++_i) \
;         __builtin_amdgcn_global_load_lds((const unsigned*)((const char*)(gbase) + (voff)[_i]), (PG8_LAS unsigned*)(lds + (bufoff) + ldsw + _i * 8192), 16, 0, PG8_AUX_##voff); } while (0)
; #define PG8_LDA(dst, b, h) do { _Pragma("unroll") for (int m = 0; m < 4; ++m) _Pragma("unroll") for (int k = 0; k < 2; ++k) dst[m][k] = *(const PG8_LAS bf16x8*)(lds + PG8_SA(b, h) + aoff + m * 2048 + k * 1024); } while (0)
; #define PG8_LDB(dst, b, h) do { _Pragma("unroll") for (int n = 0; n < 2; ++n) _Pragma("unroll") for (int k = 0; k < 2; ++k) dst[n][k] = *(const PG8_LAS bf16x8*)(lds + PG8_SB(b, h) + boff + n * 2048 + k * 1024); } while (0)
; #define PG8_WAIT_V(n) asm volatile("s_waitcnt vmcnt(" #n ")" ::: "memory")
; #define PG8_WAIT_L(n) asm volatile("s_waitcnt lgkmcnt(" #n ")" ::: "memory")
;     ...
;         for (int t = 0; t < nt; t += 2) {
;             const bool last = (t == nt - 2);
;             const char* a1 = cA + (size_t)(t + 1) * kstep;
;             const char* a2 = last ? nA : cA + (size_t)(t + 2) * kstep; const char* b2 = last ? nB : cB + (size_t)(t + 2) * kstep;
;             const char* a3 = a2 + kstep; const char* b3 = b2 + kstep;
;             if (last && has_next) S.a_ready(nxt);
;             if constexpr (SP2) {
;             PG8_LDB(B0, 0, 0); PG8_LDB(B1, 0, 1); PG8_SCHED; PG8_LDA(At, 0, 0); PG8_STAGE(PG8_SA(1, 1), a1 + hstep, voffA);
;             PG8_WAIT_V(8); PG8_WAIT_L(0); PG8_BAR; PG8_MMA(0, 0, At, B0); PG8_MMA(0, 1, At, B1); PG8_BAR; PG8_SCHED;
;             PG8_LDA(At, 0, 1); PG8_STAGE(PG8_SB(0, 0), b2, voffB); PG8_STAGE(PG8_SB(0, 1), b2 + hstep, voffB); PG8_STAGE(PG8_SA(0, 0), a2, voffA);
;             PG8_WAIT_V(8); PG8_WAIT_L(0); PG8_BAR; PG8_MMA(1, 0, At, B0); PG8_MMA(1, 1, At, B1); PG8_BAR; PG8_SCHED;
;             PG8_LDB(B0, 1, 0); PG8_LDB(B1, 1, 1); PG8_SCHED; PG8_LDA(At, 1, 0); PG8_STAGE(PG8_SA(0, 1), a2 + hstep, voffA);
;             PG8_WAIT_V(8); PG8_WAIT_L(0); PG8_BAR; PG8_MMA(0, 0, At, B0); PG8_MMA(0, 1, At, B1); PG8_BAR; PG8_SCHED;
;             PG8_LDA(At, 1, 1); PG8_STAGE(PG8_SB(1, 0), b3, voffB); PG8_STAGE(PG8_SB(1, 1), b3 + hstep, voffB); PG8_STAGE(PG8_SA(1, 0), a3, voffA);
;             PG8_WAIT_V(8); PG8_WAIT_L(0); PG8_BAR; PG8_MMA(1, 0, At, B0); PG8_MMA(1, 1, At, B1); PG8_BAR; PG8_SCHED;
.LBB0_1097:
	s_lshl_b32 s28, s57, 7
	s_add_u32 s34, s12, s28
	s_addc_u32 s35, s13, 0
	s_add_i32 s31, s57, 2
	s_lshl_b32 s36, s31, 7
	s_add_u32 s37, s12, s36
	s_addc_u32 s58, s13, 0
	s_and_b64 s[28:29], s[26:27], exec
	s_cselect_b32 s29, s11, s58
	s_cselect_b32 s28, s54, s37
	s_add_u32 s36, s4, s36
	s_addc_u32 s37, s5, 0
	s_and_b64 s[26:27], s[26:27], exec
	s_cselect_b32 s27, s15, s37
	s_cselect_b32 s26, s55, s36
	s_add_i32 s36, 0, 0x10000
	v_add_u32_e32 v138, s36, v142
	s_add_i32 s37, 0, 0x14000
	ds_read_b128 v[146:149], v138
	ds_read_b128 v[150:153], v138 offset:1024
	ds_read_b128 v[154:157], v138 offset:2048
	ds_read_b128 v[158:161], v138 offset:3072
	v_add_u32_e32 v138, s37, v142
	ds_read_b128 v[162:165], v138
	ds_read_b128 v[166:169], v138 offset:1024
	ds_read_b128 v[170:173], v138 offset:2048
	ds_read_b128 v[174:177], v138 offset:3072
	s_add_u32 s34, s34, 0x80080
	s_addc_u32 s35, s35, 0
	v_lshl_add_u64 v[138:139], s[34:35], 0, v[130:131]
	s_add_i32 m0, s44, 0xc000
	ds_read_b128 v[178:181], v144
	ds_read_b128 v[182:185], v144 offset:1024
	ds_read_b128 v[186:189], v144 offset:2048
	ds_read_b128 v[190:193], v144 offset:3072
	ds_read_b128 v[200:203], v144 offset:4096
	ds_read_b128 v[204:207], v144 offset:5120
	ds_read_b128 v[208:211], v144 offset:6144
	ds_read_b128 v[212:215], v144 offset:7168
	global_load_lds_dwordx4 v[138:139], off
	v_lshl_add_u64 v[138:139], s[34:35], 0, v[134:135]
	s_add_i32 m0, s44, 0xe000
	s_nop 0
	global_load_lds_dwordx4 v[138:139], off
	s_waitcnt vmcnt(8)
	s_waitcnt lgkmcnt(0)
	s_setprio 1
	s_barrier
	v_mfma_f32_16x16x32_bf16 v[126:129], v[146:149], v[178:181], v[126:129]
	v_mfma_f32_16x16x32_bf16 v[122:125], v[154:157], v[178:181], v[122:125]
	v_mfma_f32_16x16x32_bf16 v[118:121], v[146:149], v[186:189], v[118:121]
	v_mfma_f32_16x16x32_bf16 v[114:117], v[154:157], v[186:189], v[114:117]
	v_mfma_f32_16x16x32_bf16 v[110:113], v[146:149], v[200:203], v[110:113]
	v_mfma_f32_16x16x32_bf16 v[106:109], v[154:157], v[200:203], v[106:109]
	v_mfma_f32_16x16x32_bf16 v[102:105], v[146:149], v[208:211], v[102:105]
	v_mfma_f32_16x16x32_bf16 v[98:101], v[154:157], v[208:211], v[98:101]
	v_mfma_f32_16x16x32_bf16 v[126:129], v[150:153], v[182:185], v[126:129]
	v_mfma_f32_16x16x32_bf16 v[122:125], v[158:161], v[182:185], v[122:125]
	v_mfma_f32_16x16x32_bf16 v[118:121], v[150:153], v[190:193], v[118:121]
	v_mfma_f32_16x16x32_bf16 v[114:117], v[158:161], v[190:193], v[114:117]
	v_mfma_f32_16x16x32_bf16 v[110:113], v[150:153], v[204:207], v[110:113]
	v_mfma_f32_16x16x32_bf16 v[106:109], v[158:161], v[204:207], v[106:109]
	v_mfma_f32_16x16x32_bf16 v[102:105], v[150:153], v[212:215], v[102:105]
	v_mfma_f32_16x16x32_bf16 v[98:101], v[158:161], v[212:215], v[98:101]
	s_setprio 0
	s_setprio 1
	v_mfma_f32_16x16x32_bf16 v[94:97], v[162:165], v[178:181], v[94:97]
	v_mfma_f32_16x16x32_bf16 v[90:93], v[170:173], v[178:181], v[90:93]
	v_mfma_f32_16x16x32_bf16 v[86:89], v[162:165], v[186:189], v[86:89]
	v_mfma_f32_16x16x32_bf16 v[82:85], v[170:173], v[186:189], v[82:85]
	v_mfma_f32_16x16x32_bf16 v[78:81], v[162:165], v[200:203], v[78:81]
	v_mfma_f32_16x16x32_bf16 v[74:77], v[170:173], v[200:203], v[74:77]
	v_mfma_f32_16x16x32_bf16 v[70:73], v[162:165], v[208:211], v[70:73]
	v_mfma_f32_16x16x32_bf16 v[66:69], v[170:173], v[208:211], v[66:69]
	v_mfma_f32_16x16x32_bf16 v[94:97], v[166:169], v[182:185], v[94:97]
	v_mfma_f32_16x16x32_bf16 v[90:93], v[174:177], v[182:185], v[90:93]
	v_mfma_f32_16x16x32_bf16 v[86:89], v[166:169], v[190:193], v[86:89]
	v_mfma_f32_16x16x32_bf16 v[82:85], v[174:177], v[190:193], v[82:85]
	v_mfma_f32_16x16x32_bf16 v[78:81], v[166:169], v[204:207], v[78:81]
	v_mfma_f32_16x16x32_bf16 v[74:77], v[174:177], v[204:207], v[74:77]
	v_mfma_f32_16x16x32_bf16 v[70:73], v[166:169], v[212:215], v[70:73]
	v_mfma_f32_16x16x32_bf16 v[66:69], v[174:177], v[212:215], v[66:69]
	s_barrier
	s_setprio 0
	s_add_i32 s34, s36, s43
	v_lshl_add_u64 v[138:139], s[26:27], 0, v[132:133]
	s_mov_b32 m0, s34
	ds_read_b128 v[178:181], v144 offset:16384
	ds_read_b128 v[182:185], v144 offset:17408
	ds_read_b128 v[186:189], v144 offset:18432
	ds_read_b128 v[190:193], v144 offset:19456
	ds_read_b128 v[200:203], v144 offset:20480
	ds_read_b128 v[204:207], v144 offset:21504
	ds_read_b128 v[208:211], v144 offset:22528
	ds_read_b128 v[212:215], v144 offset:23552
	global_load_lds_dwordx4 v[138:139], off
	s_add_i32 m0, s34, 0x2000
	s_add_u32 s34, s26, 0x80000
	v_lshl_add_u64 v[220:221], s[26:27], 0, v[136:137]
	s_addc_u32 s35, s27, 0
	s_add_i32 s36, s37, s43
	global_load_lds_dwordx4 v[220:221], off
	v_lshl_add_u64 v[222:223], s[34:35], 0, v[132:133]
	s_mov_b32 m0, s36
	v_lshl_add_u64 v[230:231], s[28:29], 0, v[134:135]
	global_load_lds_dwordx4 v[222:223], off
	v_lshl_add_u64 v[222:223], s[34:35], 0, v[136:137]
	s_add_i32 m0, s36, 0x2000
	s_nop 0
	global_load_lds_dwordx4 v[222:223], off
	v_lshl_add_u64 v[222:223], s[28:29], 0, v[130:131]
	s_mov_b32 m0, s44
	s_nop 0
	global_load_lds_dwordx4 v[222:223], off
	s_mov_b32 m0, s45
	s_nop 0
	global_load_lds_dwordx4 v[230:231], off
	s_waitcnt vmcnt(8)
	s_waitcnt lgkmcnt(0)
	s_setprio 1
	s_barrier
; #define PG8_STAGE(bufoff, gbase, voff) do { _Pragma("unroll") for (int _i = 0; _i < 2; ++_i) \
;         __builtin_amdgcn_global_load_lds((const unsigned*)((const char*)(gbase) + (voff)[_i]), (PG8_LAS unsigned*)(lds + (bufoff) + ldsw + _i * 8192), 16, 0, PG8_AUX_##voff); } while (0)
; #define PG8_LDA(dst, b, h) do { _Pragma("unroll") for (int m = 0; m < 4; ++m) _Pragma("unroll") for (int k = 0; k < 2; ++k) dst[m][k] = *(const PG8_LAS bf16x8*)(lds + PG8_SA(b, h) + aoff + m * 2048 + k * 1024); } while (0)
; #define PG8_LDB(dst, b, h) do { _Pragma("unroll") for (int n = 0; n < 2; ++n) _Pragma("unroll") for (int k = 0; k < 2; ++k) dst[n][k] = *(const PG8_LAS bf16x8*)(lds + PG8_SB(b, h) + boff + n * 2048 + k * 1024); } while (0)
; #define PG8_MMA(ai, bj, At, Bt) do { __builtin_amdgcn_s_setprio(1); _Pragma("unroll") for (int m = 0; m < 4; ++m) _Pragma("unroll") for (int n = 0; n < 2; ++n) _Pragma("unroll") for (int k = 0; k < 2; ++k) \
;         acc[ai][bj][m][n] = __builtin_amdgcn_mfma_f32_16x16x32_bf16(Bt[n][k], At[m][k], acc[ai][bj][m][n], 0, 0, 0); __builtin_amdgcn_s_setprio(0); } while (0)
; #define PG8_WAIT_V(n) asm volatile("s_waitcnt vmcnt(" #n ")" ::: "memory")
; #define PG8_WAIT_L(n) asm volatile("s_waitcnt lgkmcnt(" #n ")" ::: "memory")
; #define PG8_BAR __builtin_amdgcn_s_barrier()
; #define PG8_SCHED __builtin_amdgcn_sched_barrier(0)
;     ...
;             PG8_LDA(At, 0, 1); PG8_STAGE(PG8_SB(0, 0), b2, voffB); PG8_STAGE(PG8_SB(0, 1), b2 + hstep, voffB); PG8_STAGE(PG8_SA(0, 0), a2, voffA);
;             PG8_WAIT_V(8); PG8_WAIT_L(0); PG8_BAR; PG8_MMA(1, 0, At, B0); PG8_MMA(1, 1, At, B1); PG8_BAR; PG8_SCHED;
;             PG8_LDB(B0, 1, 0); PG8_LDB(B1, 1, 1); PG8_SCHED; PG8_LDA(At, 1, 0); PG8_STAGE(PG8_SA(0, 1), a2 + hstep, voffA);
;             PG8_WAIT_V(8); PG8_WAIT_L(0); PG8_BAR; PG8_MMA(0, 0, At, B0); PG8_MMA(0, 1, At, B1); PG8_BAR; PG8_SCHED;
	v_mfma_f32_16x16x32_bf16 v[62:65], v[146:149], v[178:181], v[62:65]
	v_mfma_f32_16x16x32_bf16 v[58:61], v[154:157], v[178:181], v[58:61]
	v_mfma_f32_16x16x32_bf16 v[54:57], v[146:149], v[186:189], v[54:57]
	v_mfma_f32_16x16x32_bf16 v[50:53], v[154:157], v[186:189], v[50:53]
	v_mfma_f32_16x16x32_bf16 v[46:49], v[146:149], v[200:203], v[46:49]
	v_mfma_f32_16x16x32_bf16 v[42:45], v[154:157], v[200:203], v[42:45]
	v_mfma_f32_16x16x32_bf16 v[38:41], v[146:149], v[208:211], v[38:41]
	v_mfma_f32_16x16x32_bf16 v[34:37], v[154:157], v[208:211], v[34:37]
	v_mfma_f32_16x16x32_bf16 v[62:65], v[150:153], v[182:185], v[62:65]
	v_mfma_f32_16x16x32_bf16 v[58:61], v[158:161], v[182:185], v[58:61]
	v_mfma_f32_16x16x32_bf16 v[54:57], v[150:153], v[190:193], v[54:57]
	v_mfma_f32_16x16x32_bf16 v[50:53], v[158:161], v[190:193], v[50:53]
	v_mfma_f32_16x16x32_bf16 v[46:49], v[150:153], v[204:207], v[46:49]
	v_mfma_f32_16x16x32_bf16 v[42:45], v[158:161], v[204:207], v[42:45]
	v_mfma_f32_16x16x32_bf16 v[38:41], v[150:153], v[212:215], v[38:41]
	v_mfma_f32_16x16x32_bf16 v[34:37], v[158:161], v[212:215], v[34:37]
	s_setprio 0
	s_setprio 1
	v_mfma_f32_16x16x32_bf16 v[30:33], v[162:165], v[178:181], v[30:33]
	v_mfma_f32_16x16x32_bf16 v[26:29], v[170:173], v[178:181], v[26:29]
	v_mfma_f32_16x16x32_bf16 v[22:25], v[162:165], v[186:189], v[22:25]
	v_mfma_f32_16x16x32_bf16 v[18:21], v[170:173], v[186:189], v[18:21]
	v_mfma_f32_16x16x32_bf16 v[14:17], v[162:165], v[200:203], v[14:17]
	v_mfma_f32_16x16x32_bf16 v[10:13], v[170:173], v[200:203], v[10:13]
	v_mfma_f32_16x16x32_bf16 v[6:9], v[162:165], v[208:211], v[6:9]
	v_mfma_f32_16x16x32_bf16 v[2:5], v[170:173], v[208:211], v[2:5]
	v_mfma_f32_16x16x32_bf16 v[30:33], v[166:169], v[182:185], v[30:33]
	v_mfma_f32_16x16x32_bf16 v[26:29], v[174:177], v[182:185], v[26:29]
	v_mfma_f32_16x16x32_bf16 v[22:25], v[166:169], v[190:193], v[22:25]
	v_mfma_f32_16x16x32_bf16 v[18:21], v[174:177], v[190:193], v[18:21]
	v_mfma_f32_16x16x32_bf16 v[14:17], v[166:169], v[204:207], v[14:17]
	v_mfma_f32_16x16x32_bf16 v[10:13], v[174:177], v[204:207], v[10:13]
	v_mfma_f32_16x16x32_bf16 v[6:9], v[166:169], v[212:215], v[6:9]
	v_mfma_f32_16x16x32_bf16 v[2:5], v[174:177], v[212:215], v[2:5]
	s_barrier
	s_setprio 0
	s_add_i32 s34, 0, 0x18000
	v_add_u32_e32 v145, s34, v142
	s_add_i32 s35, 0, 0x1c000
	ds_read_b128 v[146:149], v145
	ds_read_b128 v[150:153], v145 offset:1024
	ds_read_b128 v[154:157], v145 offset:2048
	ds_read_b128 v[158:161], v145 offset:3072
	v_add_u32_e32 v145, s35, v142
	ds_read_b128 v[162:165], v145
	ds_read_b128 v[166:169], v145 offset:1024
	ds_read_b128 v[170:173], v145 offset:2048
	ds_read_b128 v[174:177], v145 offset:3072
	s_add_u32 s28, s28, 0x80000
	s_addc_u32 s29, s29, 0
	s_mov_b32 m0, s46
	v_lshl_add_u64 v[232:233], s[28:29], 0, v[130:131]
	ds_read_b128 v[178:181], v144 offset:32768
	ds_read_b128 v[182:185], v144 offset:33792
	ds_read_b128 v[186:189], v144 offset:34816
	ds_read_b128 v[190:193], v144 offset:35840
	ds_read_b128 v[200:203], v144 offset:36864
	ds_read_b128 v[204:207], v144 offset:37888
	ds_read_b128 v[208:211], v144 offset:38912
	ds_read_b128 v[212:215], v144 offset:39936
	global_load_lds_dwordx4 v[232:233], off
	v_lshl_add_u64 v[232:233], s[28:29], 0, v[134:135]
	s_mov_b32 m0, s47
	s_nop 0
	global_load_lds_dwordx4 v[232:233], off
	s_waitcnt vmcnt(8)
	s_waitcnt lgkmcnt(0)
	s_setprio 1
	s_barrier
	v_mfma_f32_16x16x32_bf16 v[126:129], v[146:149], v[178:181], v[126:129]
	v_mfma_f32_16x16x32_bf16 v[122:125], v[154:157], v[178:181], v[122:125]
	v_mfma_f32_16x16x32_bf16 v[118:121], v[146:149], v[186:189], v[118:121]
	v_mfma_f32_16x16x32_bf16 v[114:117], v[154:157], v[186:189], v[114:117]
	v_mfma_f32_16x16x32_bf16 v[110:113], v[146:149], v[200:203], v[110:113]
	v_mfma_f32_16x16x32_bf16 v[106:109], v[154:157], v[200:203], v[106:109]
	v_mfma_f32_16x16x32_bf16 v[102:105], v[146:149], v[208:211], v[102:105]
	v_mfma_f32_16x16x32_bf16 v[98:101], v[154:157], v[208:211], v[98:101]
	v_mfma_f32_16x16x32_bf16 v[126:129], v[150:153], v[182:185], v[126:129]
	v_mfma_f32_16x16x32_bf16 v[122:125], v[158:161], v[182:185], v[122:125]
	v_mfma_f32_16x16x32_bf16 v[118:121], v[150:153], v[190:193], v[118:121]
	v_mfma_f32_16x16x32_bf16 v[114:117], v[158:161], v[190:193], v[114:117]
	v_mfma_f32_16x16x32_bf16 v[110:113], v[150:153], v[204:207], v[110:113]
	v_mfma_f32_16x16x32_bf16 v[106:109], v[158:161], v[204:207], v[106:109]
	v_mfma_f32_16x16x32_bf16 v[102:105], v[150:153], v[212:215], v[102:105]
	v_mfma_f32_16x16x32_bf16 v[98:101], v[158:161], v[212:215], v[98:101]
	s_setprio 0
	s_setprio 1
	v_mfma_f32_16x16x32_bf16 v[94:97], v[162:165], v[178:181], v[94:97]
	v_mfma_f32_16x16x32_bf16 v[90:93], v[170:173], v[178:181], v[90:93]
	v_mfma_f32_16x16x32_bf16 v[86:89], v[162:165], v[186:189], v[86:89]
	v_mfma_f32_16x16x32_bf16 v[82:85], v[170:173], v[186:189], v[82:85]
	v_mfma_f32_16x16x32_bf16 v[78:81], v[162:165], v[200:203], v[78:81]
	v_mfma_f32_16x16x32_bf16 v[74:77], v[170:173], v[200:203], v[74:77]
	v_mfma_f32_16x16x32_bf16 v[70:73], v[162:165], v[208:211], v[70:73]
	v_mfma_f32_16x16x32_bf16 v[66:69], v[170:173], v[208:211], v[66:69]
	v_mfma_f32_16x16x32_bf16 v[94:97], v[166:169], v[182:185], v[94:97]
	v_mfma_f32_16x16x32_bf16 v[90:93], v[174:177], v[182:185], v[90:93]
	v_mfma_f32_16x16x32_bf16 v[86:89], v[166:169], v[190:193], v[86:89]
	v_mfma_f32_16x16x32_bf16 v[82:85], v[174:177], v[190:193], v[82:85]
	v_mfma_f32_16x16x32_bf16 v[78:81], v[166:169], v[204:207], v[78:81]
	v_mfma_f32_16x16x32_bf16 v[74:77], v[174:177], v[204:207], v[74:77]
	v_mfma_f32_16x16x32_bf16 v[70:73], v[166:169], v[212:215], v[70:73]
	v_mfma_f32_16x16x32_bf16 v[66:69], v[174:177], v[212:215], v[66:69]
	s_barrier
; #define PG8_STAGE(bufoff, gbase, voff) do { _Pragma("unroll") for (int _i = 0; _i < 2; ++_i) \
;         __builtin_amdgcn_global_load_lds((const unsigned*)((const char*)(gbase) + (voff)[_i]), (PG8_LAS unsigned*)(lds + (bufoff) + ldsw + _i * 8192), 16, 0, PG8_AUX_##voff); } while (0)
; #define PG8_LDA(dst, b, h) do { _Pragma("unroll") for (int m = 0; m < 4; ++m) _Pragma("unroll") for (int k = 0; k < 2; ++k) dst[m][k] = *(const PG8_LAS bf16x8*)(lds + PG8_SA(b, h) + aoff + m * 2048 + k * 1024); } while (0)
; #define PG8_MMA(ai, bj, At, Bt) do { __builtin_amdgcn_s_setprio(1); _Pragma("unroll") for (int m = 0; m < 4; ++m) _Pragma("unroll") for (int n = 0; n < 2; ++n) _Pragma("unroll") for (int k = 0; k < 2; ++k) \
;         acc[ai][bj][m][n] = __builtin_amdgcn_mfma_f32_16x16x32_bf16(Bt[n][k], At[m][k], acc[ai][bj][m][n], 0, 0, 0); __builtin_amdgcn_s_setprio(0); } while (0)
; #define PG8_WAIT_V(n) asm volatile("s_waitcnt vmcnt(" #n ")" ::: "memory")
; #define PG8_WAIT_L(n) asm volatile("s_waitcnt lgkmcnt(" #n ")" ::: "memory")
; #define PG8_BAR __builtin_amdgcn_s_barrier()
; #define PG8_SCHED __builtin_amdgcn_sched_barrier(0)
;     ...
;         for (int t = 0; t < nt; t += 2) {
;             const bool last = (t == nt - 2);
;     ...
;             PG8_LDA(At, 1, 1); PG8_STAGE(PG8_SB(1, 0), b3, voffB); PG8_STAGE(PG8_SB(1, 1), b3 + hstep, voffB); PG8_STAGE(PG8_SA(1, 0), a3, voffA);
;             PG8_WAIT_V(8); PG8_WAIT_L(0); PG8_BAR; PG8_MMA(1, 0, At, B0); PG8_MMA(1, 1, At, B1); PG8_BAR; PG8_SCHED;
	s_setprio 0
	s_add_i32 s28, s34, s43
	v_lshl_add_u64 v[138:139], v[138:139], 0, s[2:3]
	s_mov_b32 m0, s28
	ds_read_b128 v[178:181], v144 offset:49152
	ds_read_b128 v[182:185], v144 offset:50176
	ds_read_b128 v[186:189], v144 offset:51200
	ds_read_b128 v[190:193], v144 offset:52224
	ds_read_b128 v[200:203], v144 offset:53248
	ds_read_b128 v[204:207], v144 offset:54272
	ds_read_b128 v[208:211], v144 offset:55296
	ds_read_b128 v[212:215], v144 offset:56320
	global_load_lds_dwordx4 v[138:139], off
	s_add_i32 m0, s28, 0x2000
	s_add_u32 s26, s26, 0x80080
	v_lshl_add_u64 v[138:139], v[220:221], 0, s[2:3]
	s_addc_u32 s27, s27, 0
	s_add_i32 s28, s35, s43
	global_load_lds_dwordx4 v[138:139], off
	v_lshl_add_u64 v[138:139], s[26:27], 0, v[132:133]
	s_mov_b32 m0, s28
	s_nop 0
	global_load_lds_dwordx4 v[138:139], off
	v_lshl_add_u64 v[138:139], s[26:27], 0, v[136:137]
	s_add_i32 m0, s28, 0x2000
	s_nop 0
	global_load_lds_dwordx4 v[138:139], off
	v_lshl_add_u64 v[138:139], v[222:223], 0, s[2:3]
	s_mov_b32 m0, s48
	s_nop 0
	global_load_lds_dwordx4 v[138:139], off
	v_lshl_add_u64 v[138:139], v[230:231], 0, s[2:3]
	s_mov_b32 m0, s49
	s_nop 0
	global_load_lds_dwordx4 v[138:139], off
	s_waitcnt vmcnt(8)
	s_waitcnt lgkmcnt(0)
	s_setprio 1
	s_barrier
	v_mfma_f32_16x16x32_bf16 v[62:65], v[146:149], v[178:181], v[62:65]
	v_mfma_f32_16x16x32_bf16 v[58:61], v[154:157], v[178:181], v[58:61]
	v_mfma_f32_16x16x32_bf16 v[54:57], v[146:149], v[186:189], v[54:57]
	v_mfma_f32_16x16x32_bf16 v[50:53], v[154:157], v[186:189], v[50:53]
	v_mfma_f32_16x16x32_bf16 v[46:49], v[146:149], v[200:203], v[46:49]
	v_mfma_f32_16x16x32_bf16 v[42:45], v[154:157], v[200:203], v[42:45]
	v_mfma_f32_16x16x32_bf16 v[38:41], v[146:149], v[208:211], v[38:41]
	v_mfma_f32_16x16x32_bf16 v[34:37], v[154:157], v[208:211], v[34:37]
	v_mfma_f32_16x16x32_bf16 v[62:65], v[150:153], v[182:185], v[62:65]
	v_mfma_f32_16x16x32_bf16 v[58:61], v[158:161], v[182:185], v[58:61]
	v_mfma_f32_16x16x32_bf16 v[54:57], v[150:153], v[190:193], v[54:57]
	v_mfma_f32_16x16x32_bf16 v[50:53], v[158:161], v[190:193], v[50:53]
	v_mfma_f32_16x16x32_bf16 v[46:49], v[150:153], v[204:207], v[46:49]
	v_mfma_f32_16x16x32_bf16 v[42:45], v[158:161], v[204:207], v[42:45]
	v_mfma_f32_16x16x32_bf16 v[38:41], v[150:153], v[212:215], v[38:41]
	v_mfma_f32_16x16x32_bf16 v[34:37], v[158:161], v[212:215], v[34:37]
	s_setprio 0
	s_setprio 1
	v_mfma_f32_16x16x32_bf16 v[30:33], v[162:165], v[178:181], v[30:33]
	v_mfma_f32_16x16x32_bf16 v[26:29], v[170:173], v[178:181], v[26:29]
	v_mfma_f32_16x16x32_bf16 v[22:25], v[162:165], v[186:189], v[22:25]
	v_mfma_f32_16x16x32_bf16 v[18:21], v[170:173], v[186:189], v[18:21]
	v_mfma_f32_16x16x32_bf16 v[14:17], v[162:165], v[200:203], v[14:17]
	v_mfma_f32_16x16x32_bf16 v[10:13], v[170:173], v[200:203], v[10:13]
	v_mfma_f32_16x16x32_bf16 v[6:9], v[162:165], v[208:211], v[6:9]
	v_mfma_f32_16x16x32_bf16 v[2:5], v[170:173], v[208:211], v[2:5]
	v_mfma_f32_16x16x32_bf16 v[30:33], v[166:169], v[182:185], v[30:33]
	v_mfma_f32_16x16x32_bf16 v[26:29], v[174:177], v[182:185], v[26:29]
	v_mfma_f32_16x16x32_bf16 v[22:25], v[166:169], v[190:193], v[22:25]
	v_mfma_f32_16x16x32_bf16 v[18:21], v[174:177], v[190:193], v[18:21]
	v_mfma_f32_16x16x32_bf16 v[14:17], v[166:169], v[204:207], v[14:17]
	v_mfma_f32_16x16x32_bf16 v[10:13], v[174:177], v[204:207], v[10:13]
	v_mfma_f32_16x16x32_bf16 v[6:9], v[166:169], v[212:215], v[6:9]
	v_mfma_f32_16x16x32_bf16 v[2:5], v[174:177], v[212:215], v[2:5]
	s_barrier
	s_setprio 0
	s_cmp_gt_u32 s57, 29
	s_cbranch_scc1 .LBB0_1099
	s_mov_b32 s57, s31
	s_branch .LBB0_1080

; #define PG8_STAGE(bufoff, gbase, voff) do { _Pragma("unroll") for (int _i = 0; _i < 2; ++_i) \
;         __builtin_amdgcn_global_load_lds((const unsigned*)((const char*)(gbase) + (voff)[_i]), (PG8_LAS unsigned*)(lds + (bufoff) + ldsw + _i * 8192), 16, 0, PG8_AUX_##voff); } while (0)
; #define PG8_LDA(dst, b, h) do { _Pragma("unroll") for (int m = 0; m < 4; ++m) _Pragma("unroll") for (int k = 0; k < 2; ++k) dst[m][k] = *(const PG8_LAS bf16x8*)(lds + PG8_SA(b, h) + aoff + m * 2048 + k * 1024); } while (0)
; #define PG8_LDB(dst, b, h) do { _Pragma("unroll") for (int n = 0; n < 2; ++n) _Pragma("unroll") for (int k = 0; k < 2; ++k) dst[n][k] = *(const PG8_LAS bf16x8*)(lds + PG8_SB(b, h) + boff + n * 2048 + k * 1024); } while (0)
; #define PG8_WAIT_V(n) asm volatile("s_waitcnt vmcnt(" #n ")" ::: "memory")
; #define PG8_WAIT_L(n) asm volatile("s_waitcnt lgkmcnt(" #n ")" ::: "memory")
;     ...
;         for (int t = 0; t < nt; t += 2) {
;             const bool last = (t == nt - 2);
;             const char* a1 = cA + (size_t)(t + 1) * kstep;
;             const char* a2 = last ? nA : cA + (size_t)(t + 2) * kstep; const char* b2 = last ? nB : cB + (size_t)(t + 2) * kstep;
;             const char* a3 = a2 + kstep; const char* b3 = b2 + kstep;
;             if (last && has_next) S.a_ready(nxt);
;             if constexpr (SP2) {
;             PG8_LDB(B0, 0, 0); PG8_LDB(B1, 0, 1); PG8_SCHED; PG8_LDA(At, 0, 0); PG8_STAGE(PG8_SA(1, 1), a1 + hstep, voffA);
;             PG8_WAIT_V(8); PG8_WAIT_L(0); PG8_BAR; PG8_MMA(0, 0, At, B0); PG8_MMA(0, 1, At, B1); PG8_BAR; PG8_SCHED;
;             PG8_LDA(At, 0, 1); PG8_STAGE(PG8_SB(0, 0), b2, voffB); PG8_STAGE(PG8_SB(0, 1), b2 + hstep, voffB); PG8_STAGE(PG8_SA(0, 0), a2, voffA);
;             PG8_WAIT_V(8); PG8_WAIT_L(0); PG8_BAR; PG8_MMA(1, 0, At, B0); PG8_MMA(1, 1, At, B1); PG8_BAR; PG8_SCHED;
;             PG8_LDB(B0, 1, 0); PG8_LDB(B1, 1, 1); PG8_SCHED; PG8_LDA(At, 1, 0); PG8_STAGE(PG8_SA(0, 1), a2 + hstep, voffA);
;             PG8_WAIT_V(8); PG8_WAIT_L(0); PG8_BAR; PG8_MMA(0, 0, At, B0); PG8_MMA(0, 1, At, B1); PG8_BAR; PG8_SCHED;
;             PG8_LDA(At, 1, 1); PG8_STAGE(PG8_SB(1, 0), b3, voffB); PG8_STAGE(PG8_SB(1, 1), b3 + hstep, voffB); PG8_STAGE(PG8_SA(1, 0), a3, voffA);
;             PG8_WAIT_V(8); PG8_WAIT_L(0); PG8_BAR; PG8_MMA(1, 0, At, B0); PG8_MMA(1, 1, At, B1); PG8_BAR; PG8_SCHED;
.LBB0_1797:
	s_add_u32 s36, s28, s34
	s_addc_u32 s37, s29, s35
	s_add_u32 s60, s26, s34
	s_addc_u32 s61, s27, s35
	s_add_i32 s62, 0, 0x10000
	s_cmp_eq_u32 s13, s59
	s_cselect_b32 s39, s15, s37
	s_cselect_b32 s38, s19, s36
	s_cselect_b32 s37, s17, s61
	s_cselect_b32 s36, s58, s60
	s_add_i32 s63, 0, 0x14000
	v_add_u32_e32 v162, s62, v146
	v_add_u32_e32 v178, s63, v146
	ds_read_b128 v[150:153], v162
	ds_read_b128 v[154:157], v162 offset:1024
	ds_read_b128 v[158:161], v162 offset:2048
	ds_read_b128 v[162:165], v162 offset:3072
	ds_read_b128 v[166:169], v178
	ds_read_b128 v[170:173], v178 offset:1024
	ds_read_b128 v[174:177], v178 offset:2048
	ds_read_b128 v[178:181], v178 offset:3072
	v_lshl_add_u64 v[192:193], s[28:29], 0, v[142:143]
	s_add_i32 m0, s1, 0xc000
	ds_read_b128 v[182:185], v149
	ds_read_b128 v[188:191], v149 offset:1024
	ds_read_b128 v[200:203], v149 offset:2048
	ds_read_b128 v[204:207], v149 offset:3072
	ds_read_b128 v[208:211], v149 offset:4096
	ds_read_b128 v[212:215], v149 offset:5120
	ds_read_b128 v[220:223], v149 offset:6144
	ds_read_b128 v[230:233], v149 offset:7168
	global_load_lds_dwordx4 v[192:193], off
	v_lshl_add_u64 v[192:193], s[28:29], 0, v[140:141]
	s_add_i32 m0, s1, 0xe000
	s_nop 0
	global_load_lds_dwordx4 v[192:193], off
	s_waitcnt vmcnt(8)
	s_waitcnt lgkmcnt(0)
	s_setprio 1
	s_barrier
	v_mfma_f32_16x16x32_bf16 v[122:125], v[150:153], v[182:185], v[122:125]
	v_mfma_f32_16x16x32_bf16 v[126:129], v[158:161], v[182:185], v[126:129]
	v_mfma_f32_16x16x32_bf16 v[110:113], v[150:153], v[200:203], v[110:113]
	v_mfma_f32_16x16x32_bf16 v[106:109], v[158:161], v[200:203], v[106:109]
	v_mfma_f32_16x16x32_bf16 v[94:97], v[150:153], v[208:211], v[94:97]
	v_mfma_f32_16x16x32_bf16 v[90:93], v[158:161], v[208:211], v[90:93]
	v_mfma_f32_16x16x32_bf16 v[78:81], v[150:153], v[220:223], v[78:81]
	v_mfma_f32_16x16x32_bf16 v[74:77], v[158:161], v[220:223], v[74:77]
	v_mfma_f32_16x16x32_bf16 v[122:125], v[154:157], v[188:191], v[122:125]
	v_mfma_f32_16x16x32_bf16 v[126:129], v[162:165], v[188:191], v[126:129]
	v_mfma_f32_16x16x32_bf16 v[110:113], v[154:157], v[204:207], v[110:113]
	v_mfma_f32_16x16x32_bf16 v[106:109], v[162:165], v[204:207], v[106:109]
	v_mfma_f32_16x16x32_bf16 v[94:97], v[154:157], v[212:215], v[94:97]
	v_mfma_f32_16x16x32_bf16 v[90:93], v[162:165], v[212:215], v[90:93]
	v_mfma_f32_16x16x32_bf16 v[78:81], v[154:157], v[230:233], v[78:81]
	v_mfma_f32_16x16x32_bf16 v[74:77], v[162:165], v[230:233], v[74:77]
	s_setprio 0
	s_setprio 1
	v_mfma_f32_16x16x32_bf16 v[118:121], v[166:169], v[182:185], v[118:121]
	v_mfma_f32_16x16x32_bf16 v[114:117], v[174:177], v[182:185], v[114:117]
	v_mfma_f32_16x16x32_bf16 v[102:105], v[166:169], v[200:203], v[102:105]
	v_mfma_f32_16x16x32_bf16 v[98:101], v[174:177], v[200:203], v[98:101]
	v_mfma_f32_16x16x32_bf16 v[86:89], v[166:169], v[208:211], v[86:89]
	v_mfma_f32_16x16x32_bf16 v[82:85], v[174:177], v[208:211], v[82:85]
	v_mfma_f32_16x16x32_bf16 v[70:73], v[166:169], v[220:223], v[70:73]
	v_mfma_f32_16x16x32_bf16 v[66:69], v[174:177], v[220:223], v[66:69]
	v_mfma_f32_16x16x32_bf16 v[118:121], v[170:173], v[188:191], v[118:121]
	v_mfma_f32_16x16x32_bf16 v[114:117], v[178:181], v[188:191], v[114:117]
	v_mfma_f32_16x16x32_bf16 v[102:105], v[170:173], v[204:207], v[102:105]
	v_mfma_f32_16x16x32_bf16 v[98:101], v[178:181], v[204:207], v[98:101]
	v_mfma_f32_16x16x32_bf16 v[86:89], v[170:173], v[212:215], v[86:89]
	v_mfma_f32_16x16x32_bf16 v[82:85], v[178:181], v[212:215], v[82:85]
	v_mfma_f32_16x16x32_bf16 v[70:73], v[170:173], v[230:233], v[70:73]
	v_mfma_f32_16x16x32_bf16 v[66:69], v[178:181], v[230:233], v[66:69]
	s_barrier
	s_setprio 0
	s_add_i32 s60, s62, s42
	v_lshl_add_u64 v[192:193], s[36:37], 0, v[194:195]
	s_mov_b32 m0, s60
	ds_read_b128 v[182:185], v149 offset:16384
	ds_read_b128 v[188:191], v149 offset:17408
	ds_read_b128 v[200:203], v149 offset:18432
	ds_read_b128 v[204:207], v149 offset:19456
	ds_read_b128 v[208:211], v149 offset:20480
	ds_read_b128 v[212:215], v149 offset:21504
	ds_read_b128 v[220:223], v149 offset:22528
	ds_read_b128 v[230:233], v149 offset:23552
	global_load_lds_dwordx4 v[192:193], off
	s_add_i32 m0, s60, 0x2000
	s_add_u32 s60, s36, 0x80000
	v_lshl_add_u64 v[234:235], s[36:37], 0, v[134:135]
	s_addc_u32 s61, s37, 0
	s_add_i32 s62, s63, s42
	global_load_lds_dwordx4 v[234:235], off
	v_lshl_add_u64 v[236:237], s[60:61], 0, v[194:195]
	s_mov_b32 m0, s62
	v_lshl_add_u64 v[238:239], s[38:39], 0, v[132:133]
	global_load_lds_dwordx4 v[236:237], off
	v_lshl_add_u64 v[236:237], s[60:61], 0, v[134:135]
	s_add_i32 m0, s62, 0x2000
	s_nop 0
	global_load_lds_dwordx4 v[236:237], off
	v_lshl_add_u64 v[236:237], s[38:39], 0, v[130:131]
	s_mov_b32 m0, s1
	s_nop 0
	global_load_lds_dwordx4 v[236:237], off
	s_mov_b32 m0, s43
	s_nop 0
	global_load_lds_dwordx4 v[238:239], off
	s_waitcnt vmcnt(8)
	s_waitcnt lgkmcnt(0)
	s_setprio 1
	s_barrier
; #define PG8_STAGE(bufoff, gbase, voff) do { _Pragma("unroll") for (int _i = 0; _i < 2; ++_i) \
;         __builtin_amdgcn_global_load_lds((const unsigned*)((const char*)(gbase) + (voff)[_i]), (PG8_LAS unsigned*)(lds + (bufoff) + ldsw + _i * 8192), 16, 0, PG8_AUX_##voff); } while (0)
; #define PG8_LDA(dst, b, h) do { _Pragma("unroll") for (int m = 0; m < 4; ++m) _Pragma("unroll") for (int k = 0; k < 2; ++k) dst[m][k] = *(const PG8_LAS bf16x8*)(lds + PG8_SA(b, h) + aoff + m * 2048 + k * 1024); } while (0)
; #define PG8_LDB(dst, b, h) do { _Pragma("unroll") for (int n = 0; n < 2; ++n) _Pragma("unroll") for (int k = 0; k < 2; ++k) dst[n][k] = *(const PG8_LAS bf16x8*)(lds + PG8_SB(b, h) + boff + n * 2048 + k * 1024); } while (0)
; #define PG8_MMA(ai, bj, At, Bt) do { __builtin_amdgcn_s_setprio(1); _Pragma("unroll") for (int m = 0; m < 4; ++m) _Pragma("unroll") for (int n = 0; n < 2; ++n) _Pragma("unroll") for (int k = 0; k < 2; ++k) \
;         acc[ai][bj][m][n] = __builtin_amdgcn_mfma_f32_16x16x32_bf16(Bt[n][k], At[m][k], acc[ai][bj][m][n], 0, 0, 0); __builtin_amdgcn_s_setprio(0); } while (0)
; #define PG8_WAIT_V(n) asm volatile("s_waitcnt vmcnt(" #n ")" ::: "memory")
; #define PG8_WAIT_L(n) asm volatile("s_waitcnt lgkmcnt(" #n ")" ::: "memory")
; #define PG8_BAR __builtin_amdgcn_s_barrier()
; #define PG8_SCHED __builtin_amdgcn_sched_barrier(0)
;     ...
;             PG8_LDA(At, 0, 1); PG8_STAGE(PG8_SB(0, 0), b2, voffB); PG8_STAGE(PG8_SB(0, 1), b2 + hstep, voffB); PG8_STAGE(PG8_SA(0, 0), a2, voffA);
;             PG8_WAIT_V(8); PG8_WAIT_L(0); PG8_BAR; PG8_MMA(1, 0, At, B0); PG8_MMA(1, 1, At, B1); PG8_BAR; PG8_SCHED;
;             PG8_LDB(B0, 1, 0); PG8_LDB(B1, 1, 1); PG8_SCHED; PG8_LDA(At, 1, 0); PG8_STAGE(PG8_SA(0, 1), a2 + hstep, voffA);
;             PG8_WAIT_V(8); PG8_WAIT_L(0); PG8_BAR; PG8_MMA(0, 0, At, B0); PG8_MMA(0, 1, At, B1); PG8_BAR; PG8_SCHED;
	v_mfma_f32_16x16x32_bf16 v[62:65], v[150:153], v[182:185], v[62:65]
	v_mfma_f32_16x16x32_bf16 v[58:61], v[158:161], v[182:185], v[58:61]
	v_mfma_f32_16x16x32_bf16 v[46:49], v[150:153], v[200:203], v[46:49]
	v_mfma_f32_16x16x32_bf16 v[42:45], v[158:161], v[200:203], v[42:45]
	v_mfma_f32_16x16x32_bf16 v[30:33], v[150:153], v[208:211], v[30:33]
	v_mfma_f32_16x16x32_bf16 v[26:29], v[158:161], v[208:211], v[26:29]
	v_mfma_f32_16x16x32_bf16 v[14:17], v[150:153], v[220:223], v[14:17]
	v_mfma_f32_16x16x32_bf16 v[10:13], v[158:161], v[220:223], v[10:13]
	v_mfma_f32_16x16x32_bf16 v[62:65], v[154:157], v[188:191], v[62:65]
	v_mfma_f32_16x16x32_bf16 v[58:61], v[162:165], v[188:191], v[58:61]
	v_mfma_f32_16x16x32_bf16 v[46:49], v[154:157], v[204:207], v[46:49]
	v_mfma_f32_16x16x32_bf16 v[42:45], v[162:165], v[204:207], v[42:45]
	v_mfma_f32_16x16x32_bf16 v[30:33], v[154:157], v[212:215], v[30:33]
	v_mfma_f32_16x16x32_bf16 v[26:29], v[162:165], v[212:215], v[26:29]
	v_mfma_f32_16x16x32_bf16 v[14:17], v[154:157], v[230:233], v[14:17]
	v_mfma_f32_16x16x32_bf16 v[10:13], v[162:165], v[230:233], v[10:13]
	s_setprio 0
	s_setprio 1
	v_mfma_f32_16x16x32_bf16 v[54:57], v[166:169], v[182:185], v[54:57]
	v_mfma_f32_16x16x32_bf16 v[50:53], v[174:177], v[182:185], v[50:53]
	v_mfma_f32_16x16x32_bf16 v[38:41], v[166:169], v[200:203], v[38:41]
	v_mfma_f32_16x16x32_bf16 v[34:37], v[174:177], v[200:203], v[34:37]
	v_mfma_f32_16x16x32_bf16 v[22:25], v[166:169], v[208:211], v[22:25]
	v_mfma_f32_16x16x32_bf16 v[18:21], v[174:177], v[208:211], v[18:21]
	v_mfma_f32_16x16x32_bf16 v[6:9], v[166:169], v[220:223], v[6:9]
	v_mfma_f32_16x16x32_bf16 v[2:5], v[174:177], v[220:223], v[2:5]
	v_mfma_f32_16x16x32_bf16 v[54:57], v[170:173], v[188:191], v[54:57]
	v_mfma_f32_16x16x32_bf16 v[50:53], v[178:181], v[188:191], v[50:53]
	v_mfma_f32_16x16x32_bf16 v[38:41], v[170:173], v[204:207], v[38:41]
	v_mfma_f32_16x16x32_bf16 v[34:37], v[178:181], v[204:207], v[34:37]
	v_mfma_f32_16x16x32_bf16 v[22:25], v[170:173], v[212:215], v[22:25]
	v_mfma_f32_16x16x32_bf16 v[18:21], v[178:181], v[212:215], v[18:21]
	v_mfma_f32_16x16x32_bf16 v[6:9], v[170:173], v[230:233], v[6:9]
	v_mfma_f32_16x16x32_bf16 v[2:5], v[178:181], v[230:233], v[2:5]
	s_barrier
	s_setprio 0
	s_add_i32 s60, 0, 0x18000
	s_add_i32 s61, 0, 0x1c000
	v_add_u32_e32 v162, s60, v146
	v_add_u32_e32 v178, s61, v146
	ds_read_b128 v[150:153], v162
	ds_read_b128 v[154:157], v162 offset:1024
	ds_read_b128 v[158:161], v162 offset:2048
	ds_read_b128 v[162:165], v162 offset:3072
	ds_read_b128 v[166:169], v178
	ds_read_b128 v[170:173], v178 offset:1024
	ds_read_b128 v[174:177], v178 offset:2048
	ds_read_b128 v[178:181], v178 offset:3072
	s_add_u32 s38, s38, 0x80000
	s_addc_u32 s39, s39, 0
	s_mov_b32 m0, s44
	v_lshl_add_u64 v[240:241], s[38:39], 0, v[130:131]
	ds_read_b128 v[182:185], v149 offset:32768
	ds_read_b128 v[188:191], v149 offset:33792
	ds_read_b128 v[200:203], v149 offset:34816
	ds_read_b128 v[204:207], v149 offset:35840
	ds_read_b128 v[208:211], v149 offset:36864
	ds_read_b128 v[212:215], v149 offset:37888
	ds_read_b128 v[220:223], v149 offset:38912
	ds_read_b128 v[230:233], v149 offset:39936
	global_load_lds_dwordx4 v[240:241], off
	v_lshl_add_u64 v[240:241], s[38:39], 0, v[132:133]
	s_mov_b32 m0, s45
	s_nop 0
	global_load_lds_dwordx4 v[240:241], off
	s_waitcnt vmcnt(8)
	s_waitcnt lgkmcnt(0)
	s_setprio 1
	s_barrier
	v_mfma_f32_16x16x32_bf16 v[122:125], v[150:153], v[182:185], v[122:125]
	v_mfma_f32_16x16x32_bf16 v[126:129], v[158:161], v[182:185], v[126:129]
	v_mfma_f32_16x16x32_bf16 v[110:113], v[150:153], v[200:203], v[110:113]
	v_mfma_f32_16x16x32_bf16 v[106:109], v[158:161], v[200:203], v[106:109]
	v_mfma_f32_16x16x32_bf16 v[94:97], v[150:153], v[208:211], v[94:97]
	v_mfma_f32_16x16x32_bf16 v[90:93], v[158:161], v[208:211], v[90:93]
	v_mfma_f32_16x16x32_bf16 v[78:81], v[150:153], v[220:223], v[78:81]
	v_mfma_f32_16x16x32_bf16 v[74:77], v[158:161], v[220:223], v[74:77]
	v_mfma_f32_16x16x32_bf16 v[122:125], v[154:157], v[188:191], v[122:125]
	v_mfma_f32_16x16x32_bf16 v[126:129], v[162:165], v[188:191], v[126:129]
	v_mfma_f32_16x16x32_bf16 v[110:113], v[154:157], v[204:207], v[110:113]
	v_mfma_f32_16x16x32_bf16 v[106:109], v[162:165], v[204:207], v[106:109]
	v_mfma_f32_16x16x32_bf16 v[94:97], v[154:157], v[212:215], v[94:97]
	v_mfma_f32_16x16x32_bf16 v[90:93], v[162:165], v[212:215], v[90:93]
	v_mfma_f32_16x16x32_bf16 v[78:81], v[154:157], v[230:233], v[78:81]
	v_mfma_f32_16x16x32_bf16 v[74:77], v[162:165], v[230:233], v[74:77]
	s_setprio 0
	s_setprio 1
	v_mfma_f32_16x16x32_bf16 v[118:121], v[166:169], v[182:185], v[118:121]
	v_mfma_f32_16x16x32_bf16 v[114:117], v[174:177], v[182:185], v[114:117]
	v_mfma_f32_16x16x32_bf16 v[102:105], v[166:169], v[200:203], v[102:105]
	v_mfma_f32_16x16x32_bf16 v[98:101], v[174:177], v[200:203], v[98:101]
	v_mfma_f32_16x16x32_bf16 v[86:89], v[166:169], v[208:211], v[86:89]
	v_mfma_f32_16x16x32_bf16 v[82:85], v[174:177], v[208:211], v[82:85]
	v_mfma_f32_16x16x32_bf16 v[70:73], v[166:169], v[220:223], v[70:73]
	v_mfma_f32_16x16x32_bf16 v[66:69], v[174:177], v[220:223], v[66:69]
	v_mfma_f32_16x16x32_bf16 v[118:121], v[170:173], v[188:191], v[118:121]
	v_mfma_f32_16x16x32_bf16 v[114:117], v[178:181], v[188:191], v[114:117]
	v_mfma_f32_16x16x32_bf16 v[102:105], v[170:173], v[204:207], v[102:105]
	v_mfma_f32_16x16x32_bf16 v[98:101], v[178:181], v[204:207], v[98:101]
	v_mfma_f32_16x16x32_bf16 v[86:89], v[170:173], v[212:215], v[86:89]
	v_mfma_f32_16x16x32_bf16 v[82:85], v[178:181], v[212:215], v[82:85]
	v_mfma_f32_16x16x32_bf16 v[70:73], v[170:173], v[230:233], v[70:73]
	v_mfma_f32_16x16x32_bf16 v[66:69], v[178:181], v[230:233], v[66:69]
	s_barrier
; #define PG8_STAGE(bufoff, gbase, voff) do { _Pragma("unroll") for (int _i = 0; _i < 2; ++_i) \
;         __builtin_amdgcn_global_load_lds((const unsigned*)((const char*)(gbase) + (voff)[_i]), (PG8_LAS unsigned*)(lds + (bufoff) + ldsw + _i * 8192), 16, 0, PG8_AUX_##voff); } while (0)
; #define PG8_LDA(dst, b, h) do { _Pragma("unroll") for (int m = 0; m < 4; ++m) _Pragma("unroll") for (int k = 0; k < 2; ++k) dst[m][k] = *(const PG8_LAS bf16x8*)(lds + PG8_SA(b, h) + aoff + m * 2048 + k * 1024); } while (0)
; #define PG8_MMA(ai, bj, At, Bt) do { __builtin_amdgcn_s_setprio(1); _Pragma("unroll") for (int m = 0; m < 4; ++m) _Pragma("unroll") for (int n = 0; n < 2; ++n) _Pragma("unroll") for (int k = 0; k < 2; ++k) \
;         acc[ai][bj][m][n] = __builtin_amdgcn_mfma_f32_16x16x32_bf16(Bt[n][k], At[m][k], acc[ai][bj][m][n], 0, 0, 0); __builtin_amdgcn_s_setprio(0); } while (0)
; #define PG8_WAIT_V(n) asm volatile("s_waitcnt vmcnt(" #n ")" ::: "memory")
; #define PG8_WAIT_L(n) asm volatile("s_waitcnt lgkmcnt(" #n ")" ::: "memory")
; #define PG8_BAR __builtin_amdgcn_s_barrier()
; #define PG8_SCHED __builtin_amdgcn_sched_barrier(0)
;     ...
;         for (int t = 0; t < nt; t += 2) {
;             const bool last = (t == nt - 2);
;     ...
;             PG8_LDA(At, 1, 1); PG8_STAGE(PG8_SB(1, 0), b3, voffB); PG8_STAGE(PG8_SB(1, 1), b3 + hstep, voffB); PG8_STAGE(PG8_SA(1, 0), a3, voffA);
;             PG8_WAIT_V(8); PG8_WAIT_L(0); PG8_BAR; PG8_MMA(1, 0, At, B0); PG8_MMA(1, 1, At, B1); PG8_BAR; PG8_SCHED;
;     ...
;         if constexpr (ALIGN_EPI) { if (wr == 0) PG8_BAR; }
	s_setprio 0
	s_add_i32 s38, s60, s42
	v_lshl_add_u64 v[192:193], v[192:193], 0, s[2:3]
	s_mov_b32 m0, s38
	ds_read_b128 v[182:185], v149 offset:49152
	ds_read_b128 v[188:191], v149 offset:50176
	ds_read_b128 v[200:203], v149 offset:51200
	ds_read_b128 v[204:207], v149 offset:52224
	ds_read_b128 v[208:211], v149 offset:53248
	ds_read_b128 v[212:215], v149 offset:54272
	ds_read_b128 v[220:223], v149 offset:55296
	ds_read_b128 v[230:233], v149 offset:56320
	global_load_lds_dwordx4 v[192:193], off
	s_add_i32 m0, s38, 0x2000
	s_add_u32 s36, s36, 0x80080
	v_lshl_add_u64 v[192:193], v[234:235], 0, s[2:3]
	s_addc_u32 s37, s37, 0
	s_add_i32 s38, s61, s42
	global_load_lds_dwordx4 v[192:193], off
	v_lshl_add_u64 v[192:193], s[36:37], 0, v[194:195]
	s_mov_b32 m0, s38
	s_nop 0
	global_load_lds_dwordx4 v[192:193], off
	v_lshl_add_u64 v[192:193], s[36:37], 0, v[134:135]
	s_add_i32 m0, s38, 0x2000
	s_nop 0
	global_load_lds_dwordx4 v[192:193], off
	v_lshl_add_u64 v[192:193], v[236:237], 0, s[2:3]
	s_mov_b32 m0, s51
	s_nop 0
	global_load_lds_dwordx4 v[192:193], off
	v_lshl_add_u64 v[192:193], v[238:239], 0, s[2:3]
	s_mov_b32 m0, s52
	s_nop 0
	global_load_lds_dwordx4 v[192:193], off
	s_waitcnt vmcnt(8)
	s_waitcnt lgkmcnt(0)
	s_setprio 1
	s_barrier
	v_mfma_f32_16x16x32_bf16 v[62:65], v[150:153], v[182:185], v[62:65]
	v_mfma_f32_16x16x32_bf16 v[58:61], v[158:161], v[182:185], v[58:61]
	v_mfma_f32_16x16x32_bf16 v[46:49], v[150:153], v[200:203], v[46:49]
	v_mfma_f32_16x16x32_bf16 v[42:45], v[158:161], v[200:203], v[42:45]
	v_mfma_f32_16x16x32_bf16 v[30:33], v[150:153], v[208:211], v[30:33]
	v_mfma_f32_16x16x32_bf16 v[26:29], v[158:161], v[208:211], v[26:29]
	v_mfma_f32_16x16x32_bf16 v[14:17], v[150:153], v[220:223], v[14:17]
	v_mfma_f32_16x16x32_bf16 v[10:13], v[158:161], v[220:223], v[10:13]
	v_mfma_f32_16x16x32_bf16 v[62:65], v[154:157], v[188:191], v[62:65]
	v_mfma_f32_16x16x32_bf16 v[58:61], v[162:165], v[188:191], v[58:61]
	v_mfma_f32_16x16x32_bf16 v[46:49], v[154:157], v[204:207], v[46:49]
	v_mfma_f32_16x16x32_bf16 v[42:45], v[162:165], v[204:207], v[42:45]
	v_mfma_f32_16x16x32_bf16 v[30:33], v[154:157], v[212:215], v[30:33]
	v_mfma_f32_16x16x32_bf16 v[26:29], v[162:165], v[212:215], v[26:29]
	v_mfma_f32_16x16x32_bf16 v[14:17], v[154:157], v[230:233], v[14:17]
	v_mfma_f32_16x16x32_bf16 v[10:13], v[162:165], v[230:233], v[10:13]
	s_setprio 0
	s_setprio 1
	v_mfma_f32_16x16x32_bf16 v[54:57], v[166:169], v[182:185], v[54:57]
	v_mfma_f32_16x16x32_bf16 v[50:53], v[174:177], v[182:185], v[50:53]
	v_mfma_f32_16x16x32_bf16 v[38:41], v[166:169], v[200:203], v[38:41]
	v_mfma_f32_16x16x32_bf16 v[34:37], v[174:177], v[200:203], v[34:37]
	v_mfma_f32_16x16x32_bf16 v[22:25], v[166:169], v[208:211], v[22:25]
	v_mfma_f32_16x16x32_bf16 v[18:21], v[174:177], v[208:211], v[18:21]
	v_mfma_f32_16x16x32_bf16 v[6:9], v[166:169], v[220:223], v[6:9]
	v_mfma_f32_16x16x32_bf16 v[2:5], v[174:177], v[220:223], v[2:5]
	v_mfma_f32_16x16x32_bf16 v[54:57], v[170:173], v[188:191], v[54:57]
	v_mfma_f32_16x16x32_bf16 v[50:53], v[178:181], v[188:191], v[50:53]
	v_mfma_f32_16x16x32_bf16 v[38:41], v[170:173], v[204:207], v[38:41]
	v_mfma_f32_16x16x32_bf16 v[34:37], v[178:181], v[204:207], v[34:37]
	v_mfma_f32_16x16x32_bf16 v[22:25], v[170:173], v[212:215], v[22:25]
	v_mfma_f32_16x16x32_bf16 v[18:21], v[178:181], v[212:215], v[18:21]
	v_mfma_f32_16x16x32_bf16 v[6:9], v[170:173], v[230:233], v[6:9]
	v_mfma_f32_16x16x32_bf16 v[2:5], v[178:181], v[230:233], v[2:5]
	s_barrier
	s_setprio 0
	s_add_i32 s36, s59, 2
	s_add_u32 s34, s34, 0x100
	s_addc_u32 s35, s35, 0
	v_lshl_add_u64 v[142:143], v[142:143], 0, vcc
	v_lshl_add_u64 v[140:141], v[140:141], 0, vcc
	s_cmp_ge_i32 s59, s13
	s_mov_b32 s59, s36
	s_cbranch_scc0 .LBB0_1797
	s_and_b64 vcc, exec, s[10:11]
	s_cbranch_vccz .LBB0_1800
	s_barrier

; #define PG8_STAGE(bufoff, gbase, voff) do { _Pragma("unroll") for (int _i = 0; _i < 2; ++_i) \
;         __builtin_amdgcn_global_load_lds((const unsigned*)((const char*)(gbase) + (voff)[_i]), (PG8_LAS unsigned*)(lds + (bufoff) + ldsw + _i * 8192), 16, 0, PG8_AUX_##voff); } while (0)
; #define PG8_LDA(dst, b, h) do { _Pragma("unroll") for (int m = 0; m < 4; ++m) _Pragma("unroll") for (int k = 0; k < 2; ++k) dst[m][k] = *(const PG8_LAS bf16x8*)(lds + PG8_SA(b, h) + aoff + m * 2048 + k * 1024); } while (0)
; #define PG8_LDB(dst, b, h) do { _Pragma("unroll") for (int n = 0; n < 2; ++n) _Pragma("unroll") for (int k = 0; k < 2; ++k) dst[n][k] = *(const PG8_LAS bf16x8*)(lds + PG8_SB(b, h) + boff + n * 2048 + k * 1024); } while (0)
; #define PG8_WAIT_V(n) asm volatile("s_waitcnt vmcnt(" #n ")" ::: "memory")
; #define PG8_WAIT_L(n) asm volatile("s_waitcnt lgkmcnt(" #n ")" ::: "memory")
;     ...
;         for (int t = 0; t < nt; t += 2) {
;             const bool last = (t == nt - 2);
;             const char* a1 = cA + (size_t)(t + 1) * kstep;
;             const char* a2 = last ? nA : cA + (size_t)(t + 2) * kstep; const char* b2 = last ? nB : cB + (size_t)(t + 2) * kstep;
;             const char* a3 = a2 + kstep; const char* b3 = b2 + kstep;
;             if (last && has_next) S.a_ready(nxt);
;             if constexpr (SP2) {
;             PG8_LDB(B0, 0, 0); PG8_LDB(B1, 0, 1); PG8_SCHED; PG8_LDA(At, 0, 0); PG8_STAGE(PG8_SA(1, 1), a1 + hstep, voffA);
;             PG8_WAIT_V(8); PG8_WAIT_L(0); PG8_BAR; PG8_MMA(0, 0, At, B0); PG8_MMA(0, 1, At, B1); PG8_BAR; PG8_SCHED;
;             PG8_LDA(At, 0, 1); PG8_STAGE(PG8_SB(0, 0), b2, voffB); PG8_STAGE(PG8_SB(0, 1), b2 + hstep, voffB); PG8_STAGE(PG8_SA(0, 0), a2, voffA);
;             PG8_WAIT_V(8); PG8_WAIT_L(0); PG8_BAR; PG8_MMA(1, 0, At, B0); PG8_MMA(1, 1, At, B1); PG8_BAR; PG8_SCHED;
;             PG8_LDB(B0, 1, 0); PG8_LDB(B1, 1, 1); PG8_SCHED; PG8_LDA(At, 1, 0); PG8_STAGE(PG8_SA(0, 1), a2 + hstep, voffA);
;             PG8_WAIT_V(8); PG8_WAIT_L(0); PG8_BAR; PG8_MMA(0, 0, At, B0); PG8_MMA(0, 1, At, B1); PG8_BAR; PG8_SCHED;
;             PG8_LDA(At, 1, 1); PG8_STAGE(PG8_SB(1, 0), b3, voffB); PG8_STAGE(PG8_SB(1, 1), b3 + hstep, voffB); PG8_STAGE(PG8_SA(1, 0), a3, voffA);
;             PG8_WAIT_V(8); PG8_WAIT_L(0); PG8_BAR; PG8_MMA(1, 0, At, B0); PG8_MMA(1, 1, At, B1); PG8_BAR; PG8_SCHED;
.LBB0_2328:
	s_add_u32 s34, s28, s30
	s_addc_u32 s35, s29, s31
	s_add_u32 s59, s26, s30
	s_addc_u32 s60, s27, s31
	s_add_i32 s61, 0, 0x10000
	s_cmp_eq_u32 s21, s23
	s_cselect_b32 s37, s5, s35
	s_cselect_b32 s36, s4, s34
	v_add_u32_e32 v151, s61, v146
	s_cselect_b32 s35, s25, s60
	s_cselect_b32 s34, s24, s59
	s_add_i32 s59, 0, 0x14000
	ds_read_b128 v[152:155], v151
	ds_read_b128 v[156:159], v151 offset:1024
	ds_read_b128 v[160:163], v151 offset:2048
	ds_read_b128 v[164:167], v151 offset:3072
	v_add_u32_e32 v151, s59, v146
	ds_read_b128 v[168:171], v151
	ds_read_b128 v[172:175], v151 offset:1024
	ds_read_b128 v[176:179], v151 offset:2048
	ds_read_b128 v[180:183], v151 offset:3072
	v_lshl_add_u64 v[234:235], s[28:29], 0, v[142:143]
	s_add_i32 m0, s42, 0xc000
	ds_read_b128 v[186:189], v150
	ds_read_b128 v[190:193], v150 offset:1024
	ds_read_b128 v[200:203], v150 offset:2048
	ds_read_b128 v[204:207], v150 offset:3072
	ds_read_b128 v[208:211], v150 offset:4096
	ds_read_b128 v[212:215], v150 offset:5120
	ds_read_b128 v[220:223], v150 offset:6144
	ds_read_b128 v[230:233], v150 offset:7168
	global_load_lds_dwordx4 v[234:235], off
	v_lshl_add_u64 v[234:235], s[28:29], 0, v[140:141]
	s_add_i32 m0, s42, 0xe000
	s_nop 0
	global_load_lds_dwordx4 v[234:235], off
	s_waitcnt vmcnt(8)
	s_waitcnt lgkmcnt(0)
	s_setprio 1
	s_barrier
	v_mfma_f32_16x16x32_bf16 v[126:129], v[152:155], v[186:189], v[126:129]
	v_mfma_f32_16x16x32_bf16 v[122:125], v[160:163], v[186:189], v[122:125]
	v_mfma_f32_16x16x32_bf16 v[110:113], v[152:155], v[200:203], v[110:113]
	v_mfma_f32_16x16x32_bf16 v[106:109], v[160:163], v[200:203], v[106:109]
	v_mfma_f32_16x16x32_bf16 v[94:97], v[152:155], v[208:211], v[94:97]
	v_mfma_f32_16x16x32_bf16 v[90:93], v[160:163], v[208:211], v[90:93]
	v_mfma_f32_16x16x32_bf16 v[78:81], v[152:155], v[220:223], v[78:81]
	v_mfma_f32_16x16x32_bf16 v[74:77], v[160:163], v[220:223], v[74:77]
	v_mfma_f32_16x16x32_bf16 v[126:129], v[156:159], v[190:193], v[126:129]
	v_mfma_f32_16x16x32_bf16 v[122:125], v[164:167], v[190:193], v[122:125]
	v_mfma_f32_16x16x32_bf16 v[110:113], v[156:159], v[204:207], v[110:113]
	v_mfma_f32_16x16x32_bf16 v[106:109], v[164:167], v[204:207], v[106:109]
	v_mfma_f32_16x16x32_bf16 v[94:97], v[156:159], v[212:215], v[94:97]
	v_mfma_f32_16x16x32_bf16 v[90:93], v[164:167], v[212:215], v[90:93]
	v_mfma_f32_16x16x32_bf16 v[78:81], v[156:159], v[230:233], v[78:81]
	v_mfma_f32_16x16x32_bf16 v[74:77], v[164:167], v[230:233], v[74:77]
	s_setprio 0
	s_setprio 1
	v_mfma_f32_16x16x32_bf16 v[118:121], v[168:171], v[186:189], v[118:121]
	v_mfma_f32_16x16x32_bf16 v[114:117], v[176:179], v[186:189], v[114:117]
	v_mfma_f32_16x16x32_bf16 v[102:105], v[168:171], v[200:203], v[102:105]
	v_mfma_f32_16x16x32_bf16 v[98:101], v[176:179], v[200:203], v[98:101]
	v_mfma_f32_16x16x32_bf16 v[86:89], v[168:171], v[208:211], v[86:89]
	v_mfma_f32_16x16x32_bf16 v[82:85], v[176:179], v[208:211], v[82:85]
	v_mfma_f32_16x16x32_bf16 v[70:73], v[168:171], v[220:223], v[70:73]
	v_mfma_f32_16x16x32_bf16 v[66:69], v[176:179], v[220:223], v[66:69]
	v_mfma_f32_16x16x32_bf16 v[118:121], v[172:175], v[190:193], v[118:121]
	v_mfma_f32_16x16x32_bf16 v[114:117], v[180:183], v[190:193], v[114:117]
	v_mfma_f32_16x16x32_bf16 v[102:105], v[172:175], v[204:207], v[102:105]
	v_mfma_f32_16x16x32_bf16 v[98:101], v[180:183], v[204:207], v[98:101]
	v_mfma_f32_16x16x32_bf16 v[86:89], v[172:175], v[212:215], v[86:89]
	v_mfma_f32_16x16x32_bf16 v[82:85], v[180:183], v[212:215], v[82:85]
	v_mfma_f32_16x16x32_bf16 v[70:73], v[172:175], v[230:233], v[70:73]
	v_mfma_f32_16x16x32_bf16 v[66:69], v[180:183], v[230:233], v[66:69]
	s_barrier
	s_setprio 0
	s_add_i32 s60, s61, s41
	v_lshl_add_u64 v[234:235], s[34:35], 0, v[194:195]
	s_mov_b32 m0, s60
	ds_read_b128 v[186:189], v150 offset:16384
	ds_read_b128 v[190:193], v150 offset:17408
	ds_read_b128 v[200:203], v150 offset:18432
	ds_read_b128 v[204:207], v150 offset:19456
	ds_read_b128 v[208:211], v150 offset:20480
	ds_read_b128 v[212:215], v150 offset:21504
	ds_read_b128 v[220:223], v150 offset:22528
	ds_read_b128 v[230:233], v150 offset:23552
	global_load_lds_dwordx4 v[234:235], off
	s_add_i32 m0, s60, 0x2000
	s_add_u32 s60, s34, 0x160000
	v_lshl_add_u64 v[236:237], s[34:35], 0, v[134:135]
	s_addc_u32 s61, s35, 0
	s_add_i32 s59, s59, s41
	global_load_lds_dwordx4 v[236:237], off
	v_lshl_add_u64 v[238:239], s[60:61], 0, v[194:195]
	s_mov_b32 m0, s59
	v_lshl_add_u64 v[240:241], s[36:37], 0, v[132:133]
	global_load_lds_dwordx4 v[238:239], off
	v_lshl_add_u64 v[238:239], s[60:61], 0, v[134:135]
	s_add_i32 m0, s59, 0x2000
	s_nop 0
	global_load_lds_dwordx4 v[238:239], off
	v_lshl_add_u64 v[238:239], s[36:37], 0, v[130:131]
	s_mov_b32 m0, s42
	s_nop 0
	global_load_lds_dwordx4 v[238:239], off
	s_mov_b32 m0, s44
	s_nop 0
	global_load_lds_dwordx4 v[240:241], off
	s_waitcnt vmcnt(8)
	s_waitcnt lgkmcnt(0)
	s_setprio 1
	s_barrier
; #define PG8_STAGE(bufoff, gbase, voff) do { _Pragma("unroll") for (int _i = 0; _i < 2; ++_i) \
;         __builtin_amdgcn_global_load_lds((const unsigned*)((const char*)(gbase) + (voff)[_i]), (PG8_LAS unsigned*)(lds + (bufoff) + ldsw + _i * 8192), 16, 0, PG8_AUX_##voff); } while (0)
; #define PG8_LDA(dst, b, h) do { _Pragma("unroll") for (int m = 0; m < 4; ++m) _Pragma("unroll") for (int k = 0; k < 2; ++k) dst[m][k] = *(const PG8_LAS bf16x8*)(lds + PG8_SA(b, h) + aoff + m * 2048 + k * 1024); } while (0)
; #define PG8_LDB(dst, b, h) do { _Pragma("unroll") for (int n = 0; n < 2; ++n) _Pragma("unroll") for (int k = 0; k < 2; ++k) dst[n][k] = *(const PG8_LAS bf16x8*)(lds + PG8_SB(b, h) + boff + n * 2048 + k * 1024); } while (0)
; #define PG8_MMA(ai, bj, At, Bt) do { __builtin_amdgcn_s_setprio(1); _Pragma("unroll") for (int m = 0; m < 4; ++m) _Pragma("unroll") for (int n = 0; n < 2; ++n) _Pragma("unroll") for (int k = 0; k < 2; ++k) \
;         acc[ai][bj][m][n] = __builtin_amdgcn_mfma_f32_16x16x32_bf16(Bt[n][k], At[m][k], acc[ai][bj][m][n], 0, 0, 0); __builtin_amdgcn_s_setprio(0); } while (0)
; #define PG8_WAIT_V(n) asm volatile("s_waitcnt vmcnt(" #n ")" ::: "memory")
; #define PG8_WAIT_L(n) asm volatile("s_waitcnt lgkmcnt(" #n ")" ::: "memory")
; #define PG8_BAR __builtin_amdgcn_s_barrier()
; #define PG8_SCHED __builtin_amdgcn_sched_barrier(0)
;     ...
;             PG8_LDA(At, 0, 1); PG8_STAGE(PG8_SB(0, 0), b2, voffB); PG8_STAGE(PG8_SB(0, 1), b2 + hstep, voffB); PG8_STAGE(PG8_SA(0, 0), a2, voffA);
;             PG8_WAIT_V(8); PG8_WAIT_L(0); PG8_BAR; PG8_MMA(1, 0, At, B0); PG8_MMA(1, 1, At, B1); PG8_BAR; PG8_SCHED;
;             PG8_LDB(B0, 1, 0); PG8_LDB(B1, 1, 1); PG8_SCHED; PG8_LDA(At, 1, 0); PG8_STAGE(PG8_SA(0, 1), a2 + hstep, voffA);
;             PG8_WAIT_V(8); PG8_WAIT_L(0); PG8_BAR; PG8_MMA(0, 0, At, B0); PG8_MMA(0, 1, At, B1); PG8_BAR; PG8_SCHED;
	v_mfma_f32_16x16x32_bf16 v[62:65], v[152:155], v[186:189], v[62:65]
	v_mfma_f32_16x16x32_bf16 v[58:61], v[160:163], v[186:189], v[58:61]
	v_mfma_f32_16x16x32_bf16 v[46:49], v[152:155], v[200:203], v[46:49]
	v_mfma_f32_16x16x32_bf16 v[42:45], v[160:163], v[200:203], v[42:45]
	v_mfma_f32_16x16x32_bf16 v[30:33], v[152:155], v[208:211], v[30:33]
	v_mfma_f32_16x16x32_bf16 v[26:29], v[160:163], v[208:211], v[26:29]
	v_mfma_f32_16x16x32_bf16 v[14:17], v[152:155], v[220:223], v[14:17]
	v_mfma_f32_16x16x32_bf16 v[10:13], v[160:163], v[220:223], v[10:13]
	v_mfma_f32_16x16x32_bf16 v[62:65], v[156:159], v[190:193], v[62:65]
	v_mfma_f32_16x16x32_bf16 v[58:61], v[164:167], v[190:193], v[58:61]
	v_mfma_f32_16x16x32_bf16 v[46:49], v[156:159], v[204:207], v[46:49]
	v_mfma_f32_16x16x32_bf16 v[42:45], v[164:167], v[204:207], v[42:45]
	v_mfma_f32_16x16x32_bf16 v[30:33], v[156:159], v[212:215], v[30:33]
	v_mfma_f32_16x16x32_bf16 v[26:29], v[164:167], v[212:215], v[26:29]
	v_mfma_f32_16x16x32_bf16 v[14:17], v[156:159], v[230:233], v[14:17]
	v_mfma_f32_16x16x32_bf16 v[10:13], v[164:167], v[230:233], v[10:13]
	s_setprio 0
	s_setprio 1
	v_mfma_f32_16x16x32_bf16 v[54:57], v[168:171], v[186:189], v[54:57]
	v_mfma_f32_16x16x32_bf16 v[50:53], v[176:179], v[186:189], v[50:53]
	v_mfma_f32_16x16x32_bf16 v[38:41], v[168:171], v[200:203], v[38:41]
	v_mfma_f32_16x16x32_bf16 v[34:37], v[176:179], v[200:203], v[34:37]
	v_mfma_f32_16x16x32_bf16 v[22:25], v[168:171], v[208:211], v[22:25]
	v_mfma_f32_16x16x32_bf16 v[18:21], v[176:179], v[208:211], v[18:21]
	v_mfma_f32_16x16x32_bf16 v[6:9], v[168:171], v[220:223], v[6:9]
	v_mfma_f32_16x16x32_bf16 v[2:5], v[176:179], v[220:223], v[2:5]
	v_mfma_f32_16x16x32_bf16 v[54:57], v[172:175], v[190:193], v[54:57]
	v_mfma_f32_16x16x32_bf16 v[50:53], v[180:183], v[190:193], v[50:53]
	v_mfma_f32_16x16x32_bf16 v[38:41], v[172:175], v[204:207], v[38:41]
	v_mfma_f32_16x16x32_bf16 v[34:37], v[180:183], v[204:207], v[34:37]
	v_mfma_f32_16x16x32_bf16 v[22:25], v[172:175], v[212:215], v[22:25]
	v_mfma_f32_16x16x32_bf16 v[18:21], v[180:183], v[212:215], v[18:21]
	v_mfma_f32_16x16x32_bf16 v[6:9], v[172:175], v[230:233], v[6:9]
	v_mfma_f32_16x16x32_bf16 v[2:5], v[180:183], v[230:233], v[2:5]
	s_barrier
	s_setprio 0
	s_add_i32 s59, 0, 0x18000
	v_add_u32_e32 v151, s59, v146
	s_add_i32 s60, 0, 0x1c000
	ds_read_b128 v[152:155], v151
	ds_read_b128 v[156:159], v151 offset:1024
	ds_read_b128 v[160:163], v151 offset:2048
	ds_read_b128 v[164:167], v151 offset:3072
	v_add_u32_e32 v151, s60, v146
	ds_read_b128 v[168:171], v151
	ds_read_b128 v[172:175], v151 offset:1024
	ds_read_b128 v[176:179], v151 offset:2048
	ds_read_b128 v[180:183], v151 offset:3072
	s_add_u32 s36, s36, 0x160000
	s_addc_u32 s37, s37, 0
	s_mov_b32 m0, s45
	v_lshl_add_u64 v[242:243], s[36:37], 0, v[130:131]
	ds_read_b128 v[186:189], v150 offset:32768
	ds_read_b128 v[190:193], v150 offset:33792
	ds_read_b128 v[200:203], v150 offset:34816
	ds_read_b128 v[204:207], v150 offset:35840
	ds_read_b128 v[208:211], v150 offset:36864
	ds_read_b128 v[212:215], v150 offset:37888
	ds_read_b128 v[220:223], v150 offset:38912
	ds_read_b128 v[230:233], v150 offset:39936
	global_load_lds_dwordx4 v[242:243], off
	v_lshl_add_u64 v[242:243], s[36:37], 0, v[132:133]
	s_mov_b32 m0, s46
	s_nop 0
	global_load_lds_dwordx4 v[242:243], off
	s_waitcnt vmcnt(8)
	s_waitcnt lgkmcnt(0)
	s_setprio 1
	s_barrier
	v_mfma_f32_16x16x32_bf16 v[126:129], v[152:155], v[186:189], v[126:129]
	v_mfma_f32_16x16x32_bf16 v[122:125], v[160:163], v[186:189], v[122:125]
	v_mfma_f32_16x16x32_bf16 v[110:113], v[152:155], v[200:203], v[110:113]
	v_mfma_f32_16x16x32_bf16 v[106:109], v[160:163], v[200:203], v[106:109]
	v_mfma_f32_16x16x32_bf16 v[94:97], v[152:155], v[208:211], v[94:97]
	v_mfma_f32_16x16x32_bf16 v[90:93], v[160:163], v[208:211], v[90:93]
	v_mfma_f32_16x16x32_bf16 v[78:81], v[152:155], v[220:223], v[78:81]
	v_mfma_f32_16x16x32_bf16 v[74:77], v[160:163], v[220:223], v[74:77]
	v_mfma_f32_16x16x32_bf16 v[126:129], v[156:159], v[190:193], v[126:129]
	v_mfma_f32_16x16x32_bf16 v[122:125], v[164:167], v[190:193], v[122:125]
	v_mfma_f32_16x16x32_bf16 v[110:113], v[156:159], v[204:207], v[110:113]
	v_mfma_f32_16x16x32_bf16 v[106:109], v[164:167], v[204:207], v[106:109]
	v_mfma_f32_16x16x32_bf16 v[94:97], v[156:159], v[212:215], v[94:97]
	v_mfma_f32_16x16x32_bf16 v[90:93], v[164:167], v[212:215], v[90:93]
	v_mfma_f32_16x16x32_bf16 v[78:81], v[156:159], v[230:233], v[78:81]
	v_mfma_f32_16x16x32_bf16 v[74:77], v[164:167], v[230:233], v[74:77]
	s_setprio 0
	s_setprio 1
	v_mfma_f32_16x16x32_bf16 v[118:121], v[168:171], v[186:189], v[118:121]
	v_mfma_f32_16x16x32_bf16 v[114:117], v[176:179], v[186:189], v[114:117]
	v_mfma_f32_16x16x32_bf16 v[102:105], v[168:171], v[200:203], v[102:105]
	v_mfma_f32_16x16x32_bf16 v[98:101], v[176:179], v[200:203], v[98:101]
	v_mfma_f32_16x16x32_bf16 v[86:89], v[168:171], v[208:211], v[86:89]
	v_mfma_f32_16x16x32_bf16 v[82:85], v[176:179], v[208:211], v[82:85]
	v_mfma_f32_16x16x32_bf16 v[70:73], v[168:171], v[220:223], v[70:73]
	v_mfma_f32_16x16x32_bf16 v[66:69], v[176:179], v[220:223], v[66:69]
	v_mfma_f32_16x16x32_bf16 v[118:121], v[172:175], v[190:193], v[118:121]
	v_mfma_f32_16x16x32_bf16 v[114:117], v[180:183], v[190:193], v[114:117]
	v_mfma_f32_16x16x32_bf16 v[102:105], v[172:175], v[204:207], v[102:105]
	v_mfma_f32_16x16x32_bf16 v[98:101], v[180:183], v[204:207], v[98:101]
	v_mfma_f32_16x16x32_bf16 v[86:89], v[172:175], v[212:215], v[86:89]
	v_mfma_f32_16x16x32_bf16 v[82:85], v[180:183], v[212:215], v[82:85]
	v_mfma_f32_16x16x32_bf16 v[70:73], v[172:175], v[230:233], v[70:73]
	v_mfma_f32_16x16x32_bf16 v[66:69], v[180:183], v[230:233], v[66:69]
	s_barrier
; #define PG8_STAGE(bufoff, gbase, voff) do { _Pragma("unroll") for (int _i = 0; _i < 2; ++_i) \
;         __builtin_amdgcn_global_load_lds((const unsigned*)((const char*)(gbase) + (voff)[_i]), (PG8_LAS unsigned*)(lds + (bufoff) + ldsw + _i * 8192), 16, 0, PG8_AUX_##voff); } while (0)
; #define PG8_LDA(dst, b, h) do { _Pragma("unroll") for (int m = 0; m < 4; ++m) _Pragma("unroll") for (int k = 0; k < 2; ++k) dst[m][k] = *(const PG8_LAS bf16x8*)(lds + PG8_SA(b, h) + aoff + m * 2048 + k * 1024); } while (0)
; #define PG8_MMA(ai, bj, At, Bt) do { __builtin_amdgcn_s_setprio(1); _Pragma("unroll") for (int m = 0; m < 4; ++m) _Pragma("unroll") for (int n = 0; n < 2; ++n) _Pragma("unroll") for (int k = 0; k < 2; ++k) \
;         acc[ai][bj][m][n] = __builtin_amdgcn_mfma_f32_16x16x32_bf16(Bt[n][k], At[m][k], acc[ai][bj][m][n], 0, 0, 0); __builtin_amdgcn_s_setprio(0); } while (0)
; #define PG8_WAIT_V(n) asm volatile("s_waitcnt vmcnt(" #n ")" ::: "memory")
; #define PG8_WAIT_L(n) asm volatile("s_waitcnt lgkmcnt(" #n ")" ::: "memory")
; #define PG8_BAR __builtin_amdgcn_s_barrier()
; #define PG8_SCHED __builtin_amdgcn_sched_barrier(0)
;     ...
;         for (int t = 0; t < nt; t += 2) {
;             const bool last = (t == nt - 2);
;     ...
;             PG8_LDA(At, 1, 1); PG8_STAGE(PG8_SB(1, 0), b3, voffB); PG8_STAGE(PG8_SB(1, 1), b3 + hstep, voffB); PG8_STAGE(PG8_SA(1, 0), a3, voffA);
;             PG8_WAIT_V(8); PG8_WAIT_L(0); PG8_BAR; PG8_MMA(1, 0, At, B0); PG8_MMA(1, 1, At, B1); PG8_BAR; PG8_SCHED;
;     ...
;         if constexpr (ALIGN_EPI) { if (wr == 0) PG8_BAR; }
	s_setprio 0
	s_add_i32 s36, s59, s41
	v_lshl_add_u64 v[234:235], v[234:235], 0, s[2:3]
	s_mov_b32 m0, s36
	ds_read_b128 v[186:189], v150 offset:49152
	ds_read_b128 v[190:193], v150 offset:50176
	ds_read_b128 v[200:203], v150 offset:51200
	ds_read_b128 v[204:207], v150 offset:52224
	ds_read_b128 v[208:211], v150 offset:53248
	ds_read_b128 v[212:215], v150 offset:54272
	ds_read_b128 v[220:223], v150 offset:55296
	ds_read_b128 v[230:233], v150 offset:56320
	global_load_lds_dwordx4 v[234:235], off
	s_add_i32 m0, s36, 0x2000
	s_add_u32 s34, s34, 0x160080
	v_lshl_add_u64 v[234:235], v[236:237], 0, s[2:3]
	s_addc_u32 s35, s35, 0
	s_add_i32 s36, s60, s41
	global_load_lds_dwordx4 v[234:235], off
	v_lshl_add_u64 v[234:235], s[34:35], 0, v[194:195]
	s_mov_b32 m0, s36
	s_nop 0
	global_load_lds_dwordx4 v[234:235], off
	v_lshl_add_u64 v[234:235], s[34:35], 0, v[134:135]
	s_add_i32 m0, s36, 0x2000
	s_nop 0
	global_load_lds_dwordx4 v[234:235], off
	v_lshl_add_u64 v[234:235], v[238:239], 0, s[2:3]
	s_mov_b32 m0, s47
	s_nop 0
	global_load_lds_dwordx4 v[234:235], off
	v_lshl_add_u64 v[234:235], v[240:241], 0, s[2:3]
	s_mov_b32 m0, s52
	s_nop 0
	global_load_lds_dwordx4 v[234:235], off
	s_waitcnt vmcnt(8)
	s_waitcnt lgkmcnt(0)
	s_setprio 1
	s_barrier
	v_mfma_f32_16x16x32_bf16 v[62:65], v[152:155], v[186:189], v[62:65]
	v_mfma_f32_16x16x32_bf16 v[58:61], v[160:163], v[186:189], v[58:61]
	v_mfma_f32_16x16x32_bf16 v[46:49], v[152:155], v[200:203], v[46:49]
	v_mfma_f32_16x16x32_bf16 v[42:45], v[160:163], v[200:203], v[42:45]
	v_mfma_f32_16x16x32_bf16 v[30:33], v[152:155], v[208:211], v[30:33]
	v_mfma_f32_16x16x32_bf16 v[26:29], v[160:163], v[208:211], v[26:29]
	v_mfma_f32_16x16x32_bf16 v[14:17], v[152:155], v[220:223], v[14:17]
	v_mfma_f32_16x16x32_bf16 v[10:13], v[160:163], v[220:223], v[10:13]
	v_mfma_f32_16x16x32_bf16 v[62:65], v[156:159], v[190:193], v[62:65]
	v_mfma_f32_16x16x32_bf16 v[58:61], v[164:167], v[190:193], v[58:61]
	v_mfma_f32_16x16x32_bf16 v[46:49], v[156:159], v[204:207], v[46:49]
	v_mfma_f32_16x16x32_bf16 v[42:45], v[164:167], v[204:207], v[42:45]
	v_mfma_f32_16x16x32_bf16 v[30:33], v[156:159], v[212:215], v[30:33]
	v_mfma_f32_16x16x32_bf16 v[26:29], v[164:167], v[212:215], v[26:29]
	v_mfma_f32_16x16x32_bf16 v[14:17], v[156:159], v[230:233], v[14:17]
	v_mfma_f32_16x16x32_bf16 v[10:13], v[164:167], v[230:233], v[10:13]
	s_setprio 0
	s_setprio 1
	v_mfma_f32_16x16x32_bf16 v[54:57], v[168:171], v[186:189], v[54:57]
	v_mfma_f32_16x16x32_bf16 v[50:53], v[176:179], v[186:189], v[50:53]
	v_mfma_f32_16x16x32_bf16 v[38:41], v[168:171], v[200:203], v[38:41]
	v_mfma_f32_16x16x32_bf16 v[34:37], v[176:179], v[200:203], v[34:37]
	v_mfma_f32_16x16x32_bf16 v[22:25], v[168:171], v[208:211], v[22:25]
	v_mfma_f32_16x16x32_bf16 v[18:21], v[176:179], v[208:211], v[18:21]
	v_mfma_f32_16x16x32_bf16 v[6:9], v[168:171], v[220:223], v[6:9]
	v_mfma_f32_16x16x32_bf16 v[2:5], v[176:179], v[220:223], v[2:5]
	v_mfma_f32_16x16x32_bf16 v[54:57], v[172:175], v[190:193], v[54:57]
	v_mfma_f32_16x16x32_bf16 v[50:53], v[180:183], v[190:193], v[50:53]
	v_mfma_f32_16x16x32_bf16 v[38:41], v[172:175], v[204:207], v[38:41]
	v_mfma_f32_16x16x32_bf16 v[34:37], v[180:183], v[204:207], v[34:37]
	v_mfma_f32_16x16x32_bf16 v[22:25], v[172:175], v[212:215], v[22:25]
	v_mfma_f32_16x16x32_bf16 v[18:21], v[180:183], v[212:215], v[18:21]
	v_mfma_f32_16x16x32_bf16 v[6:9], v[172:175], v[230:233], v[6:9]
	v_mfma_f32_16x16x32_bf16 v[2:5], v[180:183], v[230:233], v[2:5]
	s_barrier
	s_setprio 0
	s_add_i32 s34, s23, 2
	s_add_u32 s30, s30, 0x100
	s_addc_u32 s31, s31, 0
	v_lshl_add_u64 v[142:143], v[142:143], 0, s[62:63]
	v_lshl_add_u64 v[140:141], v[140:141], 0, s[62:63]
	s_cmp_ge_i32 s23, s21
	s_mov_b32 s23, s34
	s_cbranch_scc0 .LBB0_2328
	s_and_b64 vcc, exec, s[18:19]
	s_cbranch_vccz .LBB0_2331
	s_barrier
